# P1 unified job loop: pair blocks and single tiles in one per-XCD job list (pairs x,x+6,x+12 + singles 42/47 on XCD 0-5; singles + pair 18 row-grouped on XCD 6/7), conv workgroups get 6 pairs
# baseline (speedup 1.0000x reference)
; #define MFMA32(a, b, c) __builtin_amdgcn_mfma_f32_32x32x16_bf16((a), (b), (c), 0, 0, 0)
; template <bool SWAP, class Epi>
; DI void gemm_tile(const u16* __restrict__ A, int lda, const u16* __restrict__ Bw, int ldb, int K, char* lds, Epi epi) {
;     ...
;   const int lrow = tid >> 3, lkc = tid & 7;
;   u32x4 ra0[4], rb0[2], ra1[4], rb1[2];
;   const u16* ap = A + (size_t)lrow * lda + lkc * 8;
;   const u16* bp = Bw + (size_t)lrow * ldb + lkc * 8;
;   const int nk = K >> 6;
;   auto gload = [&](int kt, u32x4* ra, u32x4* rb) {
; #pragma unroll
;     for (int j = 0; j < 4; ++j) ra[j] = *(const u32x4*)(ap + (size_t)(64 * j) * lda + kt * 64);
; #pragma unroll
;     for (int j = 0; j < 2; ++j) rb[j] = *(const u32x4*)(bp + (size_t)(64 * j) * ldb + kt * 64);
;   };
;   auto lstore = [&](int st, const u32x4* ra, const u32x4* rb) {
;     char* base = lds + st * GEMM_STAGE;
; #pragma unroll
;     for (int j = 0; j < 4; ++j) *(u32x4*)(base + ((lrow + 64 * j) * 72 + lkc * 8) * 2) = ra[j];
; #pragma unroll
;     for (int j = 0; j < 2; ++j) *(u32x4*)(base + 36864 + ((lrow + 64 * j) * 72 + lkc * 8) * 2) = rb[j];
;   };
;   auto compute = [&](int st) {
;     const char* as = lds + st * GEMM_STAGE;
;     const char* bs = as + 36864;
; #pragma unroll
;     for (int ks = 0; ks < 4; ++ks) {
;       bf16x8 af[2], bfr[2];
; #pragma unroll
;       for (int mi = 0; mi < 2; ++mi) af[mi] = *(const bf16x8*)(as + ((wm * 64 + mi * 32 + r) * 72 + ks * 16 + 8 * h) * 2);
; #pragma unroll
;       for (int ni = 0; ni < 2; ++ni) bfr[ni] = *(const bf16x8*)(bs + ((wn * 64 + ni * 32 + r) * 72 + ks * 16 + 8 * h) * 2);
; #pragma unroll
;       for (int mi = 0; mi < 2; ++mi)
; #pragma unroll
;         for (int ni = 0; ni < 2; ++ni) {
;           if (SWAP) acc[mi][ni] = MFMA32(bfr[ni], af[mi], acc[mi][ni]);
;           else acc[mi][ni] = MFMA32(af[mi], bfr[ni], acc[mi][ni]);
;         }
;     }
;   };
;   gload(0, ra0, rb0);
;   lstore(0, ra0, rb0);
;   gload(1, ra1, rb1);
;   __syncthreads();
;   for (int kt = 0; kt < nk; kt += 2) {
;     if (kt + 2 < nk) gload(kt + 2, ra0, rb0);
;     compute(0);
; __global__ void __launch_bounds__(NTHREADS) mega(Params p) {
;     ...
;       for (int j = blockIdx.x; j < 66 * 48; j += gridDim.x) inproj_tile(p, l, j / 48, j % 48, lds);
.LBB0_320:
	v_readlane_b32 s0, v240, 17
	v_readlane_b32 s1, v240, 18
	s_andn2_b64 vcc, exec, s[0:1]
	s_lshl_b32 s0, s38, 4
	s_lshl_b32 s50, s38, 3
	v_writelane_b32 v238, s0, 45
	s_nop 1
	v_writelane_b32 v238, s1, 46
	s_cbranch_vccnz .LBB0_370
	s_bitcmp1_b32 s38, 0
	v_readlane_b32 s4, v241, 16
	s_cselect_b32 s0, 0xc00000, 0
	s_add_u32 s18, s4, s0
	v_readlane_b32 s0, v238, 45
	v_readlane_b32 s5, v241, 17
	s_addc_u32 s19, s5, 0
	s_mov_b32 s1, s61
	s_mov_b32 s2, s0
	v_writelane_b32 v238, s2, 45
	s_lshl_b64 s[0:1], s[0:1], 2
	v_readlane_b32 s6, v241, 42
	v_writelane_b32 v238, s3, 46
	v_readlane_b32 s7, v241, 43
	v_readlane_b32 s10, v241, 46
	s_add_u32 s20, s6, s0
	s_addc_u32 s21, s7, s1
	s_lshl_b32 s22, s10, 7
	v_readlane_b32 s23, v238, 17
	v_readlane_b32 s24, v238, 15
	v_readlane_b32 s25, v238, 16
	s_lshr_b32 s25, s25, 3
	s_branch .LBB0_324
.Lpp_body:
	s_waitcnt lgkmcnt(0)
	s_barrier
	s_lshl_b32 s1, s0, 1
	s_cmp_gt_u32 s0, 1
	s_cselect_b32 s2, 4, 0
	s_add_i32 s2, s1, s2
	v_readlane_b32 s4, v241, 26
	v_readlane_b32 s5, v241, 27
	v_readlane_b32 s8, v241, 24
	v_readlane_b32 s9, v241, 25
	v_lshrrev_b32_e32 v0, 6, v152
	v_and_b32_e32 v1, 63, v152
	s_lshl_b32 s0, s26, 19
	s_add_u32 s4, s4, s0
	s_addc_u32 s5, s5, 0
	s_lshl_b32 s0, s2, 18
	s_add_u32 s6, s18, s0
	s_addc_u32 s7, s19, 0
	v_readfirstlane_b32 s3, v0
	s_lshl_b32 s0, s3, 16
	s_add_u32 s68, s4, s0
	s_addc_u32 s69, s5, 0
	s_add_u32 s70, s68, 0x3c00
	s_addc_u32 s71, s69, 0
	s_add_u32 s72, s70, 0x3c00
	s_addc_u32 s73, s71, 0
	s_add_u32 s74, s72, 0x3c00
	s_addc_u32 s75, s73, 0
	s_add_u32 s76, s6, s0
	s_addc_u32 s77, s7, 0
	s_add_u32 s78, s76, 0x3c00
	s_addc_u32 s79, s77, 0
	s_add_u32 s80, s78, 0x3c00
	s_addc_u32 s81, s79, 0
	s_add_u32 s82, s80, 0x3c00
	s_addc_u32 s83, s81, 0
	s_lshl_b32 s40, s3, 12
	s_add_i32 s44, s40, 0
	s_add_i32 s45, s40, 0x8000
	s_add_i32 s46, s40, 0x10000
	s_add_i32 s47, s40, 0x18000
	v_lshrrev_b32_e32 v2, 4, v1
	v_and_b32_e32 v0, 7, v1
	v_xor_b32_e32 v2, v2, v0
	v_lshlrev_b32_e32 v2, 4, v2
	v_lshrrev_b32_e32 v0, 3, v1
	v_lshlrev_b32_e32 v0, 11, v0
	v_add_u32_e32 v208, v2, v0
	v_xor_b32_e32 v209, 64, v208
	s_mov_b32 m0, s44
	s_nop 0
	global_load_lds_dwordx4 v208, s[68:69]
	global_load_lds_dwordx4 v209, s[70:71] offset:1024
	global_load_lds_dwordx4 v208, s[72:73] offset:2048
	global_load_lds_dwordx4 v209, s[74:75] offset:3072
	s_mov_b32 m0, s46
	s_nop 0
	global_load_lds_dwordx4 v208, s[76:77]
	global_load_lds_dwordx4 v209, s[78:79] offset:1024
	global_load_lds_dwordx4 v208, s[80:81] offset:2048
	global_load_lds_dwordx4 v209, s[82:83] offset:3072
	v_add_u32_e32 v208, 0x80, v208
	v_add_u32_e32 v209, 0x80, v209
	v_and_b32_e32 v0, 31, v1
	v_lshrrev_b32_e32 v2, 1, v0
	v_and_b32_e32 v2, 7, v2
	v_lshrrev_b32_e32 v1, 5, v1
	v_xor_b32_e32 v2, v2, v1
	v_lshlrev_b32_e32 v0, 7, v0
	s_and_b32 s0, s3, 3
	s_lshr_b32 s1, s3, 2
	s_lshl_b32 s10, s0, 13
	s_lshl_b32 s11, s1, 13
	s_add_i32 s11, s11, 0x10000
	v_xor_b32_e32 v214, 0, v2
	v_lshl_add_u32 v214, v214, 4, v0
	v_add_u32_e32 v210, s10, v214
	v_add_u32_e32 v214, s11, v214
	v_xor_b32_e32 v215, 2, v2
	v_lshl_add_u32 v215, v215, 4, v0
	v_add_u32_e32 v211, s10, v215
	v_add_u32_e32 v215, s11, v215
	v_xor_b32_e32 v216, 4, v2
	v_lshl_add_u32 v216, v216, 4, v0
	v_add_u32_e32 v212, s10, v216
	v_add_u32_e32 v216, s11, v216
	v_xor_b32_e32 v217, 6, v2
	v_lshl_add_u32 v217, v217, 4, v0
	v_add_u32_e32 v213, s10, v217
	v_add_u32_e32 v217, s11, v217
	s_lshl_b32 s12, s26, 8
	s_lshl_b32 s0, s0, 6
	s_add_i32 s12, s12, s0
	v_lshrrev_b32_e32 v0, 7, v0
	v_add_u32_e32 v0, s12, v0
	v_mul_u32_u24_e32 v0, 0x2a00, v0
	s_lshl_b32 s12, s2, 8
	s_lshl_b32 s1, s1, 7
	s_add_i32 s12, s12, s1
	v_lshlrev_b32_e32 v1, 4, v1
	v_add3_u32 v218, v0, v1, s12
	v_add_u32_e32 v219, 0x54000, v218
	s_waitcnt vmcnt(0) lgkmcnt(0)
	s_barrier
	ds_read_b128 v[132:135], v210 offset:0
	ds_read_b128 v[136:139], v210 offset:4096
	ds_read_b128 v[140:143], v214 offset:0
	ds_read_b128 v[144:147], v214 offset:4096
	ds_read_b128 v[148:151], v214 offset:16384
	ds_read_b128 v[158:161], v214 offset:20480
	s_mov_b32 m0, s45
	s_nop 0
	global_load_lds_dwordx4 v208, s[68:69]
	global_load_lds_dwordx4 v209, s[70:71] offset:1024
	global_load_lds_dwordx4 v208, s[72:73] offset:2048
	global_load_lds_dwordx4 v209, s[74:75] offset:3072
	ds_read_b128 v[162:165], v211 offset:0
	ds_read_b128 v[168:171], v211 offset:4096
	ds_read_b128 v[172:175], v215 offset:0
	ds_read_b128 v[176:179], v215 offset:4096
	ds_read_b128 v[180:183], v215 offset:16384
	ds_read_b128 v[184:187], v215 offset:20480
	s_waitcnt lgkmcnt(6)
	v_mfma_f32_32x32x16_bf16 v[4:19], v[140:143], v[132:135], 0
	v_mfma_f32_32x32x16_bf16 v[68:83], v[140:143], v[136:139], 0
	v_mfma_f32_32x32x16_bf16 v[20:35], v[144:147], v[132:135], 0
	v_mfma_f32_32x32x16_bf16 v[84:99], v[144:147], v[136:139], 0
	v_mfma_f32_32x32x16_bf16 v[36:51], v[148:151], v[132:135], 0
	v_mfma_f32_32x32x16_bf16 v[100:115], v[148:151], v[136:139], 0
	v_mfma_f32_32x32x16_bf16 v[52:67], v[158:161], v[132:135], 0
	v_mfma_f32_32x32x16_bf16 v[116:131], v[158:161], v[136:139], 0
	s_mov_b32 m0, s47
	s_nop 0
	global_load_lds_dwordx4 v208, s[76:77]
	global_load_lds_dwordx4 v209, s[78:79] offset:1024
	global_load_lds_dwordx4 v208, s[80:81] offset:2048
	global_load_lds_dwordx4 v209, s[82:83] offset:3072
	v_add_u32_e32 v208, 0x80, v208
	v_add_u32_e32 v209, 0x80, v209
	ds_read_b128 v[132:135], v212 offset:0
	ds_read_b128 v[136:139], v212 offset:4096
	ds_read_b128 v[140:143], v216 offset:0
	ds_read_b128 v[144:147], v216 offset:4096
	ds_read_b128 v[148:151], v216 offset:16384
	ds_read_b128 v[158:161], v216 offset:20480
	s_waitcnt lgkmcnt(6)
; #define MFMA32(a, b, c) __builtin_amdgcn_mfma_f32_32x32x16_bf16((a), (b), (c), 0, 0, 0)
; template <bool SWAP, class Epi>
; DI void gemm_tile(const u16* __restrict__ A, int lda, const u16* __restrict__ Bw, int ldb, int K, char* lds, Epi epi) {
;     ...
;     for (int ks = 0; ks < 4; ++ks) {
;       bf16x8 af[2], bfr[2];
; #pragma unroll
;       for (int mi = 0; mi < 2; ++mi) af[mi] = *(const bf16x8*)(as + ((wm * 64 + mi * 32 + r) * 72 + ks * 16 + 8 * h) * 2);
; #pragma unroll
;       for (int ni = 0; ni < 2; ++ni) bfr[ni] = *(const bf16x8*)(bs + ((wn * 64 + ni * 32 + r) * 72 + ks * 16 + 8 * h) * 2);
; #pragma unroll
;       for (int mi = 0; mi < 2; ++mi)
; #pragma unroll
;         for (int ni = 0; ni < 2; ++ni) {
;           if (SWAP) acc[mi][ni] = MFMA32(bfr[ni], af[mi], acc[mi][ni]);
;           else acc[mi][ni] = MFMA32(af[mi], bfr[ni], acc[mi][ni]);
;         }
;     }
;   };
;   gload(0, ra0, rb0);
;   lstore(0, ra0, rb0);
;   gload(1, ra1, rb1);
;   __syncthreads();
;   for (int kt = 0; kt < nk; kt += 2) {
;     if (kt + 2 < nk) gload(kt + 2, ra0, rb0);
;     compute(0);
;     lstore(1, ra1, rb1);
;     __syncthreads();
;     if (kt + 3 < nk) gload(kt + 3, ra1, rb1);
;     compute(1);
;     if (kt + 2 < nk) lstore(0, ra0, rb0);
;     __syncthreads();
	v_mfma_f32_32x32x16_bf16 v[4:19], v[172:175], v[162:165], v[4:19]
	v_mfma_f32_32x32x16_bf16 v[68:83], v[172:175], v[168:171], v[68:83]
	v_mfma_f32_32x32x16_bf16 v[20:35], v[176:179], v[162:165], v[20:35]
	v_mfma_f32_32x32x16_bf16 v[84:99], v[176:179], v[168:171], v[84:99]
	v_mfma_f32_32x32x16_bf16 v[36:51], v[180:183], v[162:165], v[36:51]
	v_mfma_f32_32x32x16_bf16 v[100:115], v[180:183], v[168:171], v[100:115]
	v_mfma_f32_32x32x16_bf16 v[52:67], v[184:187], v[162:165], v[52:67]
	v_mfma_f32_32x32x16_bf16 v[116:131], v[184:187], v[168:171], v[116:131]
	ds_read_b128 v[162:165], v213 offset:0
	ds_read_b128 v[168:171], v213 offset:4096
	ds_read_b128 v[172:175], v217 offset:0
	ds_read_b128 v[176:179], v217 offset:4096
	ds_read_b128 v[180:183], v217 offset:16384
	ds_read_b128 v[184:187], v217 offset:20480
	s_waitcnt lgkmcnt(6)
	v_mfma_f32_32x32x16_bf16 v[4:19], v[140:143], v[132:135], v[4:19]
	v_mfma_f32_32x32x16_bf16 v[68:83], v[140:143], v[136:139], v[68:83]
	v_mfma_f32_32x32x16_bf16 v[20:35], v[144:147], v[132:135], v[20:35]
	v_mfma_f32_32x32x16_bf16 v[84:99], v[144:147], v[136:139], v[84:99]
	v_mfma_f32_32x32x16_bf16 v[36:51], v[148:151], v[132:135], v[36:51]
	v_mfma_f32_32x32x16_bf16 v[100:115], v[148:151], v[136:139], v[100:115]
	v_mfma_f32_32x32x16_bf16 v[52:67], v[158:161], v[132:135], v[52:67]
	v_mfma_f32_32x32x16_bf16 v[116:131], v[158:161], v[136:139], v[116:131]
	s_waitcnt lgkmcnt(0)
	v_mfma_f32_32x32x16_bf16 v[4:19], v[172:175], v[162:165], v[4:19]
	v_mfma_f32_32x32x16_bf16 v[68:83], v[172:175], v[168:171], v[68:83]
	v_mfma_f32_32x32x16_bf16 v[20:35], v[176:179], v[162:165], v[20:35]
	v_mfma_f32_32x32x16_bf16 v[84:99], v[176:179], v[168:171], v[84:99]
	v_mfma_f32_32x32x16_bf16 v[36:51], v[180:183], v[162:165], v[36:51]
	v_mfma_f32_32x32x16_bf16 v[100:115], v[180:183], v[168:171], v[100:115]
	v_mfma_f32_32x32x16_bf16 v[52:67], v[184:187], v[162:165], v[52:67]
	v_mfma_f32_32x32x16_bf16 v[116:131], v[184:187], v[168:171], v[116:131]
	s_waitcnt vmcnt(0) lgkmcnt(0)
	s_barrier
	ds_read_b128 v[132:135], v210 offset:32768
	ds_read_b128 v[136:139], v210 offset:36864
	ds_read_b128 v[140:143], v214 offset:32768
	ds_read_b128 v[144:147], v214 offset:36864
	ds_read_b128 v[148:151], v214 offset:49152
	ds_read_b128 v[158:161], v214 offset:53248
	s_mov_b32 m0, s44
	s_nop 0
	global_load_lds_dwordx4 v208, s[68:69]
	global_load_lds_dwordx4 v209, s[70:71] offset:1024
	global_load_lds_dwordx4 v208, s[72:73] offset:2048
	global_load_lds_dwordx4 v209, s[74:75] offset:3072
	ds_read_b128 v[162:165], v211 offset:32768
	ds_read_b128 v[168:171], v211 offset:36864
	ds_read_b128 v[172:175], v215 offset:32768
	ds_read_b128 v[176:179], v215 offset:36864
	ds_read_b128 v[180:183], v215 offset:49152
	ds_read_b128 v[184:187], v215 offset:53248
	s_waitcnt lgkmcnt(6)
	v_mfma_f32_32x32x16_bf16 v[4:19], v[140:143], v[132:135], v[4:19]
	v_mfma_f32_32x32x16_bf16 v[68:83], v[140:143], v[136:139], v[68:83]
	v_mfma_f32_32x32x16_bf16 v[20:35], v[144:147], v[132:135], v[20:35]
	v_mfma_f32_32x32x16_bf16 v[84:99], v[144:147], v[136:139], v[84:99]
	v_mfma_f32_32x32x16_bf16 v[36:51], v[148:151], v[132:135], v[36:51]
	v_mfma_f32_32x32x16_bf16 v[100:115], v[148:151], v[136:139], v[100:115]
	v_mfma_f32_32x32x16_bf16 v[52:67], v[158:161], v[132:135], v[52:67]
	v_mfma_f32_32x32x16_bf16 v[116:131], v[158:161], v[136:139], v[116:131]
	s_mov_b32 m0, s46
	s_nop 0
	global_load_lds_dwordx4 v208, s[76:77]
	global_load_lds_dwordx4 v209, s[78:79] offset:1024
	global_load_lds_dwordx4 v208, s[80:81] offset:2048
	global_load_lds_dwordx4 v209, s[82:83] offset:3072
	v_add_u32_e32 v208, 0x80, v208
	v_add_u32_e32 v209, 0x80, v209
	ds_read_b128 v[132:135], v212 offset:32768
	ds_read_b128 v[136:139], v212 offset:36864
	ds_read_b128 v[140:143], v216 offset:32768
	ds_read_b128 v[144:147], v216 offset:36864
	ds_read_b128 v[148:151], v216 offset:49152
	ds_read_b128 v[158:161], v216 offset:53248
	s_waitcnt lgkmcnt(6)
	v_mfma_f32_32x32x16_bf16 v[4:19], v[172:175], v[162:165], v[4:19]
	v_mfma_f32_32x32x16_bf16 v[68:83], v[172:175], v[168:171], v[68:83]
	v_mfma_f32_32x32x16_bf16 v[20:35], v[176:179], v[162:165], v[20:35]
	v_mfma_f32_32x32x16_bf16 v[84:99], v[176:179], v[168:171], v[84:99]
	v_mfma_f32_32x32x16_bf16 v[36:51], v[180:183], v[162:165], v[36:51]
	v_mfma_f32_32x32x16_bf16 v[100:115], v[180:183], v[168:171], v[100:115]
	v_mfma_f32_32x32x16_bf16 v[52:67], v[184:187], v[162:165], v[52:67]
	v_mfma_f32_32x32x16_bf16 v[116:131], v[184:187], v[168:171], v[116:131]
	ds_read_b128 v[162:165], v213 offset:32768
	ds_read_b128 v[168:171], v213 offset:36864
	ds_read_b128 v[172:175], v217 offset:32768
	ds_read_b128 v[176:179], v217 offset:36864
	ds_read_b128 v[180:183], v217 offset:49152
	ds_read_b128 v[184:187], v217 offset:53248
	s_waitcnt lgkmcnt(6)
	v_mfma_f32_32x32x16_bf16 v[4:19], v[140:143], v[132:135], v[4:19]
	v_mfma_f32_32x32x16_bf16 v[68:83], v[140:143], v[136:139], v[68:83]
	v_mfma_f32_32x32x16_bf16 v[20:35], v[144:147], v[132:135], v[20:35]
	v_mfma_f32_32x32x16_bf16 v[84:99], v[144:147], v[136:139], v[84:99]
	v_mfma_f32_32x32x16_bf16 v[36:51], v[148:151], v[132:135], v[36:51]
	v_mfma_f32_32x32x16_bf16 v[100:115], v[148:151], v[136:139], v[100:115]
	v_mfma_f32_32x32x16_bf16 v[52:67], v[158:161], v[132:135], v[52:67]
	v_mfma_f32_32x32x16_bf16 v[116:131], v[158:161], v[136:139], v[116:131]
	s_waitcnt lgkmcnt(0)
	v_mfma_f32_32x32x16_bf16 v[4:19], v[172:175], v[162:165], v[4:19]
	v_mfma_f32_32x32x16_bf16 v[68:83], v[172:175], v[168:171], v[68:83]
	v_mfma_f32_32x32x16_bf16 v[20:35], v[176:179], v[162:165], v[20:35]
	v_mfma_f32_32x32x16_bf16 v[84:99], v[176:179], v[168:171], v[84:99]
	v_mfma_f32_32x32x16_bf16 v[36:51], v[180:183], v[162:165], v[36:51]
	v_mfma_f32_32x32x16_bf16 v[100:115], v[180:183], v[168:171], v[100:115]
	v_mfma_f32_32x32x16_bf16 v[52:67], v[184:187], v[162:165], v[52:67]
	v_mfma_f32_32x32x16_bf16 v[116:131], v[184:187], v[168:171], v[116:131]
	s_waitcnt vmcnt(0) lgkmcnt(0)
	s_barrier
; #define MFMA32(a, b, c) __builtin_amdgcn_mfma_f32_32x32x16_bf16((a), (b), (c), 0, 0, 0)
; template <bool SWAP, class Epi>
; DI void gemm_tile(const u16* __restrict__ A, int lda, const u16* __restrict__ Bw, int ldb, int K, char* lds, Epi epi) {
;     ...
;     for (int ks = 0; ks < 4; ++ks) {
;       bf16x8 af[2], bfr[2];
; #pragma unroll
;       for (int mi = 0; mi < 2; ++mi) af[mi] = *(const bf16x8*)(as + ((wm * 64 + mi * 32 + r) * 72 + ks * 16 + 8 * h) * 2);
; #pragma unroll
;       for (int ni = 0; ni < 2; ++ni) bfr[ni] = *(const bf16x8*)(bs + ((wn * 64 + ni * 32 + r) * 72 + ks * 16 + 8 * h) * 2);
; #pragma unroll
;       for (int mi = 0; mi < 2; ++mi)
; #pragma unroll
;         for (int ni = 0; ni < 2; ++ni) {
;           if (SWAP) acc[mi][ni] = MFMA32(bfr[ni], af[mi], acc[mi][ni]);
;           else acc[mi][ni] = MFMA32(af[mi], bfr[ni], acc[mi][ni]);
;         }
;     }
;   };
;   gload(0, ra0, rb0);
;   lstore(0, ra0, rb0);
;   gload(1, ra1, rb1);
;   __syncthreads();
;   for (int kt = 0; kt < nk; kt += 2) {
;     if (kt + 2 < nk) gload(kt + 2, ra0, rb0);
;     compute(0);
;     lstore(1, ra1, rb1);
;     __syncthreads();
;     if (kt + 3 < nk) gload(kt + 3, ra1, rb1);
;     compute(1);
;     if (kt + 2 < nk) lstore(0, ra0, rb0);
;     __syncthreads();
	ds_read_b128 v[132:135], v210 offset:0
	ds_read_b128 v[136:139], v210 offset:4096
	ds_read_b128 v[140:143], v214 offset:0
	ds_read_b128 v[144:147], v214 offset:4096
	ds_read_b128 v[148:151], v214 offset:16384
	ds_read_b128 v[158:161], v214 offset:20480
	s_mov_b32 m0, s45
	s_nop 0
	global_load_lds_dwordx4 v208, s[68:69]
	global_load_lds_dwordx4 v209, s[70:71] offset:1024
	global_load_lds_dwordx4 v208, s[72:73] offset:2048
	global_load_lds_dwordx4 v209, s[74:75] offset:3072
	ds_read_b128 v[162:165], v211 offset:0
	ds_read_b128 v[168:171], v211 offset:4096
	ds_read_b128 v[172:175], v215 offset:0
	ds_read_b128 v[176:179], v215 offset:4096
	ds_read_b128 v[180:183], v215 offset:16384
	ds_read_b128 v[184:187], v215 offset:20480
	s_waitcnt lgkmcnt(6)
	v_mfma_f32_32x32x16_bf16 v[4:19], v[140:143], v[132:135], v[4:19]
	v_mfma_f32_32x32x16_bf16 v[68:83], v[140:143], v[136:139], v[68:83]
	v_mfma_f32_32x32x16_bf16 v[20:35], v[144:147], v[132:135], v[20:35]
	v_mfma_f32_32x32x16_bf16 v[84:99], v[144:147], v[136:139], v[84:99]
	v_mfma_f32_32x32x16_bf16 v[36:51], v[148:151], v[132:135], v[36:51]
	v_mfma_f32_32x32x16_bf16 v[100:115], v[148:151], v[136:139], v[100:115]
	v_mfma_f32_32x32x16_bf16 v[52:67], v[158:161], v[132:135], v[52:67]
	v_mfma_f32_32x32x16_bf16 v[116:131], v[158:161], v[136:139], v[116:131]
	s_mov_b32 m0, s47
	s_nop 0
	global_load_lds_dwordx4 v208, s[76:77]
	global_load_lds_dwordx4 v209, s[78:79] offset:1024
	global_load_lds_dwordx4 v208, s[80:81] offset:2048
	global_load_lds_dwordx4 v209, s[82:83] offset:3072
	v_add_u32_e32 v208, 0x80, v208
	v_add_u32_e32 v209, 0x80, v209
	ds_read_b128 v[132:135], v212 offset:0
	ds_read_b128 v[136:139], v212 offset:4096
	ds_read_b128 v[140:143], v216 offset:0
	ds_read_b128 v[144:147], v216 offset:4096
	ds_read_b128 v[148:151], v216 offset:16384
	ds_read_b128 v[158:161], v216 offset:20480
	s_waitcnt lgkmcnt(6)
	v_mfma_f32_32x32x16_bf16 v[4:19], v[172:175], v[162:165], v[4:19]
	v_mfma_f32_32x32x16_bf16 v[68:83], v[172:175], v[168:171], v[68:83]
	v_mfma_f32_32x32x16_bf16 v[20:35], v[176:179], v[162:165], v[20:35]
	v_mfma_f32_32x32x16_bf16 v[84:99], v[176:179], v[168:171], v[84:99]
	v_mfma_f32_32x32x16_bf16 v[36:51], v[180:183], v[162:165], v[36:51]
	v_mfma_f32_32x32x16_bf16 v[100:115], v[180:183], v[168:171], v[100:115]
	v_mfma_f32_32x32x16_bf16 v[52:67], v[184:187], v[162:165], v[52:67]
	v_mfma_f32_32x32x16_bf16 v[116:131], v[184:187], v[168:171], v[116:131]
	ds_read_b128 v[162:165], v213 offset:0
	ds_read_b128 v[168:171], v213 offset:4096
	ds_read_b128 v[172:175], v217 offset:0
	ds_read_b128 v[176:179], v217 offset:4096
	ds_read_b128 v[180:183], v217 offset:16384
	ds_read_b128 v[184:187], v217 offset:20480
	s_waitcnt lgkmcnt(6)
	v_mfma_f32_32x32x16_bf16 v[4:19], v[140:143], v[132:135], v[4:19]
	v_mfma_f32_32x32x16_bf16 v[68:83], v[140:143], v[136:139], v[68:83]
	v_mfma_f32_32x32x16_bf16 v[20:35], v[144:147], v[132:135], v[20:35]
	v_mfma_f32_32x32x16_bf16 v[84:99], v[144:147], v[136:139], v[84:99]
	v_mfma_f32_32x32x16_bf16 v[36:51], v[148:151], v[132:135], v[36:51]
	v_mfma_f32_32x32x16_bf16 v[100:115], v[148:151], v[136:139], v[100:115]
	v_mfma_f32_32x32x16_bf16 v[52:67], v[158:161], v[132:135], v[52:67]
	v_mfma_f32_32x32x16_bf16 v[116:131], v[158:161], v[136:139], v[116:131]
	s_waitcnt lgkmcnt(0)
	v_mfma_f32_32x32x16_bf16 v[4:19], v[172:175], v[162:165], v[4:19]
	v_mfma_f32_32x32x16_bf16 v[68:83], v[172:175], v[168:171], v[68:83]
	v_mfma_f32_32x32x16_bf16 v[20:35], v[176:179], v[162:165], v[20:35]
	v_mfma_f32_32x32x16_bf16 v[84:99], v[176:179], v[168:171], v[84:99]
	v_mfma_f32_32x32x16_bf16 v[36:51], v[180:183], v[162:165], v[36:51]
	v_mfma_f32_32x32x16_bf16 v[100:115], v[180:183], v[168:171], v[100:115]
	v_mfma_f32_32x32x16_bf16 v[52:67], v[184:187], v[162:165], v[52:67]
	v_mfma_f32_32x32x16_bf16 v[116:131], v[184:187], v[168:171], v[116:131]
	s_waitcnt vmcnt(0) lgkmcnt(0)
	s_barrier
	ds_read_b128 v[132:135], v210 offset:32768
	ds_read_b128 v[136:139], v210 offset:36864
	ds_read_b128 v[140:143], v214 offset:32768
	ds_read_b128 v[144:147], v214 offset:36864
	ds_read_b128 v[148:151], v214 offset:49152
	ds_read_b128 v[158:161], v214 offset:53248
	s_mov_b32 m0, s44
	s_nop 0
	global_load_lds_dwordx4 v208, s[68:69]
	global_load_lds_dwordx4 v209, s[70:71] offset:1024
	global_load_lds_dwordx4 v208, s[72:73] offset:2048
	global_load_lds_dwordx4 v209, s[74:75] offset:3072
	ds_read_b128 v[162:165], v211 offset:32768
	ds_read_b128 v[168:171], v211 offset:36864
	ds_read_b128 v[172:175], v215 offset:32768
	ds_read_b128 v[176:179], v215 offset:36864
	ds_read_b128 v[180:183], v215 offset:49152
	ds_read_b128 v[184:187], v215 offset:53248
	s_waitcnt lgkmcnt(6)
	v_mfma_f32_32x32x16_bf16 v[4:19], v[140:143], v[132:135], v[4:19]
	v_mfma_f32_32x32x16_bf16 v[68:83], v[140:143], v[136:139], v[68:83]
	v_mfma_f32_32x32x16_bf16 v[20:35], v[144:147], v[132:135], v[20:35]
	v_mfma_f32_32x32x16_bf16 v[84:99], v[144:147], v[136:139], v[84:99]
	v_mfma_f32_32x32x16_bf16 v[36:51], v[148:151], v[132:135], v[36:51]
	v_mfma_f32_32x32x16_bf16 v[100:115], v[148:151], v[136:139], v[100:115]
	v_mfma_f32_32x32x16_bf16 v[52:67], v[158:161], v[132:135], v[52:67]
	v_mfma_f32_32x32x16_bf16 v[116:131], v[158:161], v[136:139], v[116:131]
	s_mov_b32 m0, s46
	s_nop 0
	global_load_lds_dwordx4 v208, s[76:77]
	global_load_lds_dwordx4 v209, s[78:79] offset:1024
	global_load_lds_dwordx4 v208, s[80:81] offset:2048
	global_load_lds_dwordx4 v209, s[82:83] offset:3072
	v_add_u32_e32 v208, 0x80, v208
	v_add_u32_e32 v209, 0x80, v209
	ds_read_b128 v[132:135], v212 offset:32768
	ds_read_b128 v[136:139], v212 offset:36864
	ds_read_b128 v[140:143], v216 offset:32768
	ds_read_b128 v[144:147], v216 offset:36864
	ds_read_b128 v[148:151], v216 offset:49152
	ds_read_b128 v[158:161], v216 offset:53248
	s_waitcnt lgkmcnt(6)
; #define MFMA32(a, b, c) __builtin_amdgcn_mfma_f32_32x32x16_bf16((a), (b), (c), 0, 0, 0)
; template <bool SWAP, class Epi>
; DI void gemm_tile(const u16* __restrict__ A, int lda, const u16* __restrict__ Bw, int ldb, int K, char* lds, Epi epi) {
;     ...
;   auto compute = [&](int st) {
;     const char* as = lds + st * GEMM_STAGE;
;     const char* bs = as + 36864;
; #pragma unroll
;     for (int ks = 0; ks < 4; ++ks) {
;       bf16x8 af[2], bfr[2];
; #pragma unroll
;       for (int mi = 0; mi < 2; ++mi) af[mi] = *(const bf16x8*)(as + ((wm * 64 + mi * 32 + r) * 72 + ks * 16 + 8 * h) * 2);
; #pragma unroll
;       for (int ni = 0; ni < 2; ++ni) bfr[ni] = *(const bf16x8*)(bs + ((wn * 64 + ni * 32 + r) * 72 + ks * 16 + 8 * h) * 2);
; #pragma unroll
;       for (int mi = 0; mi < 2; ++mi)
; #pragma unroll
;         for (int ni = 0; ni < 2; ++ni) {
;           if (SWAP) acc[mi][ni] = MFMA32(bfr[ni], af[mi], acc[mi][ni]);
;           else acc[mi][ni] = MFMA32(af[mi], bfr[ni], acc[mi][ni]);
;         }
;     }
;   };
;   gload(0, ra0, rb0);
;   lstore(0, ra0, rb0);
;   gload(1, ra1, rb1);
;   __syncthreads();
;   for (int kt = 0; kt < nk; kt += 2) {
;     if (kt + 2 < nk) gload(kt + 2, ra0, rb0);
;     compute(0);
;     lstore(1, ra1, rb1);
;     __syncthreads();
;     if (kt + 3 < nk) gload(kt + 3, ra1, rb1);
;     compute(1);
;     if (kt + 2 < nk) lstore(0, ra0, rb0);
;     __syncthreads();
	v_mfma_f32_32x32x16_bf16 v[4:19], v[172:175], v[162:165], v[4:19]
	v_mfma_f32_32x32x16_bf16 v[68:83], v[172:175], v[168:171], v[68:83]
	v_mfma_f32_32x32x16_bf16 v[20:35], v[176:179], v[162:165], v[20:35]
	v_mfma_f32_32x32x16_bf16 v[84:99], v[176:179], v[168:171], v[84:99]
	v_mfma_f32_32x32x16_bf16 v[36:51], v[180:183], v[162:165], v[36:51]
	v_mfma_f32_32x32x16_bf16 v[100:115], v[180:183], v[168:171], v[100:115]
	v_mfma_f32_32x32x16_bf16 v[52:67], v[184:187], v[162:165], v[52:67]
	v_mfma_f32_32x32x16_bf16 v[116:131], v[184:187], v[168:171], v[116:131]
	ds_read_b128 v[162:165], v213 offset:32768
	ds_read_b128 v[168:171], v213 offset:36864
	ds_read_b128 v[172:175], v217 offset:32768
	ds_read_b128 v[176:179], v217 offset:36864
	ds_read_b128 v[180:183], v217 offset:49152
	ds_read_b128 v[184:187], v217 offset:53248
	s_waitcnt lgkmcnt(6)
	v_mfma_f32_32x32x16_bf16 v[4:19], v[140:143], v[132:135], v[4:19]
	v_mfma_f32_32x32x16_bf16 v[68:83], v[140:143], v[136:139], v[68:83]
	v_mfma_f32_32x32x16_bf16 v[20:35], v[144:147], v[132:135], v[20:35]
	v_mfma_f32_32x32x16_bf16 v[84:99], v[144:147], v[136:139], v[84:99]
	v_mfma_f32_32x32x16_bf16 v[36:51], v[148:151], v[132:135], v[36:51]
	v_mfma_f32_32x32x16_bf16 v[100:115], v[148:151], v[136:139], v[100:115]
	v_mfma_f32_32x32x16_bf16 v[52:67], v[158:161], v[132:135], v[52:67]
	v_mfma_f32_32x32x16_bf16 v[116:131], v[158:161], v[136:139], v[116:131]
	s_waitcnt lgkmcnt(0)
	v_mfma_f32_32x32x16_bf16 v[4:19], v[172:175], v[162:165], v[4:19]
	v_mfma_f32_32x32x16_bf16 v[68:83], v[172:175], v[168:171], v[68:83]
	v_mfma_f32_32x32x16_bf16 v[20:35], v[176:179], v[162:165], v[20:35]
	v_mfma_f32_32x32x16_bf16 v[84:99], v[176:179], v[168:171], v[84:99]
	v_mfma_f32_32x32x16_bf16 v[36:51], v[180:183], v[162:165], v[36:51]
	v_mfma_f32_32x32x16_bf16 v[100:115], v[180:183], v[168:171], v[100:115]
	v_mfma_f32_32x32x16_bf16 v[52:67], v[184:187], v[162:165], v[52:67]
	v_mfma_f32_32x32x16_bf16 v[116:131], v[184:187], v[168:171], v[116:131]
	s_waitcnt vmcnt(0) lgkmcnt(0)
	s_barrier
	ds_read_b128 v[132:135], v210 offset:0
	ds_read_b128 v[136:139], v210 offset:4096
	ds_read_b128 v[140:143], v214 offset:0
	ds_read_b128 v[144:147], v214 offset:4096
	ds_read_b128 v[148:151], v214 offset:16384
	ds_read_b128 v[158:161], v214 offset:20480
	s_mov_b32 m0, s45
	s_nop 0
	global_load_lds_dwordx4 v208, s[68:69]
	global_load_lds_dwordx4 v209, s[70:71] offset:1024
	global_load_lds_dwordx4 v208, s[72:73] offset:2048
	global_load_lds_dwordx4 v209, s[74:75] offset:3072
	ds_read_b128 v[162:165], v211 offset:0
	ds_read_b128 v[168:171], v211 offset:4096
	ds_read_b128 v[172:175], v215 offset:0
	ds_read_b128 v[176:179], v215 offset:4096
	ds_read_b128 v[180:183], v215 offset:16384
	ds_read_b128 v[184:187], v215 offset:20480
	s_waitcnt lgkmcnt(6)
	v_mfma_f32_32x32x16_bf16 v[4:19], v[140:143], v[132:135], v[4:19]
	v_mfma_f32_32x32x16_bf16 v[68:83], v[140:143], v[136:139], v[68:83]
	v_mfma_f32_32x32x16_bf16 v[20:35], v[144:147], v[132:135], v[20:35]
	v_mfma_f32_32x32x16_bf16 v[84:99], v[144:147], v[136:139], v[84:99]
	v_mfma_f32_32x32x16_bf16 v[36:51], v[148:151], v[132:135], v[36:51]
	v_mfma_f32_32x32x16_bf16 v[100:115], v[148:151], v[136:139], v[100:115]
	v_mfma_f32_32x32x16_bf16 v[52:67], v[158:161], v[132:135], v[52:67]
	v_mfma_f32_32x32x16_bf16 v[116:131], v[158:161], v[136:139], v[116:131]
	s_mov_b32 m0, s47
	s_nop 0
	global_load_lds_dwordx4 v208, s[76:77]
	global_load_lds_dwordx4 v209, s[78:79] offset:1024
	global_load_lds_dwordx4 v208, s[80:81] offset:2048
	global_load_lds_dwordx4 v209, s[82:83] offset:3072
	v_add_u32_e32 v208, 0x80, v208
	v_add_u32_e32 v209, 0x80, v209
	ds_read_b128 v[132:135], v212 offset:0
	ds_read_b128 v[136:139], v212 offset:4096
	ds_read_b128 v[140:143], v216 offset:0
	ds_read_b128 v[144:147], v216 offset:4096
	ds_read_b128 v[148:151], v216 offset:16384
	ds_read_b128 v[158:161], v216 offset:20480
	s_waitcnt lgkmcnt(6)
	v_mfma_f32_32x32x16_bf16 v[4:19], v[172:175], v[162:165], v[4:19]
	v_mfma_f32_32x32x16_bf16 v[68:83], v[172:175], v[168:171], v[68:83]
	v_mfma_f32_32x32x16_bf16 v[20:35], v[176:179], v[162:165], v[20:35]
	v_mfma_f32_32x32x16_bf16 v[84:99], v[176:179], v[168:171], v[84:99]
	v_mfma_f32_32x32x16_bf16 v[36:51], v[180:183], v[162:165], v[36:51]
	v_mfma_f32_32x32x16_bf16 v[100:115], v[180:183], v[168:171], v[100:115]
	v_mfma_f32_32x32x16_bf16 v[52:67], v[184:187], v[162:165], v[52:67]
	v_mfma_f32_32x32x16_bf16 v[116:131], v[184:187], v[168:171], v[116:131]
	ds_read_b128 v[162:165], v213 offset:0
	ds_read_b128 v[168:171], v213 offset:4096
	ds_read_b128 v[172:175], v217 offset:0
	ds_read_b128 v[176:179], v217 offset:4096
	ds_read_b128 v[180:183], v217 offset:16384
	ds_read_b128 v[184:187], v217 offset:20480
	s_waitcnt lgkmcnt(6)
	v_mfma_f32_32x32x16_bf16 v[4:19], v[140:143], v[132:135], v[4:19]
	v_mfma_f32_32x32x16_bf16 v[68:83], v[140:143], v[136:139], v[68:83]
	v_mfma_f32_32x32x16_bf16 v[20:35], v[144:147], v[132:135], v[20:35]
	v_mfma_f32_32x32x16_bf16 v[84:99], v[144:147], v[136:139], v[84:99]
	v_mfma_f32_32x32x16_bf16 v[36:51], v[148:151], v[132:135], v[36:51]
	v_mfma_f32_32x32x16_bf16 v[100:115], v[148:151], v[136:139], v[100:115]
	v_mfma_f32_32x32x16_bf16 v[52:67], v[158:161], v[132:135], v[52:67]
	v_mfma_f32_32x32x16_bf16 v[116:131], v[158:161], v[136:139], v[116:131]
	s_waitcnt lgkmcnt(0)
	v_mfma_f32_32x32x16_bf16 v[4:19], v[172:175], v[162:165], v[4:19]
	v_mfma_f32_32x32x16_bf16 v[68:83], v[172:175], v[168:171], v[68:83]
	v_mfma_f32_32x32x16_bf16 v[20:35], v[176:179], v[162:165], v[20:35]
	v_mfma_f32_32x32x16_bf16 v[84:99], v[176:179], v[168:171], v[84:99]
	v_mfma_f32_32x32x16_bf16 v[36:51], v[180:183], v[162:165], v[36:51]
	v_mfma_f32_32x32x16_bf16 v[100:115], v[180:183], v[168:171], v[100:115]
	v_mfma_f32_32x32x16_bf16 v[52:67], v[184:187], v[162:165], v[52:67]
	v_mfma_f32_32x32x16_bf16 v[116:131], v[184:187], v[168:171], v[116:131]
	s_waitcnt vmcnt(0) lgkmcnt(0)
	s_barrier
; #define MFMA32(a, b, c) __builtin_amdgcn_mfma_f32_32x32x16_bf16((a), (b), (c), 0, 0, 0)
; template <bool SWAP, class Epi>
; DI void gemm_tile(const u16* __restrict__ A, int lda, const u16* __restrict__ Bw, int ldb, int K, char* lds, Epi epi) {
;     ...
;   auto compute = [&](int st) {
;     const char* as = lds + st * GEMM_STAGE;
;     const char* bs = as + 36864;
; #pragma unroll
;     for (int ks = 0; ks < 4; ++ks) {
;       bf16x8 af[2], bfr[2];
; #pragma unroll
;       for (int mi = 0; mi < 2; ++mi) af[mi] = *(const bf16x8*)(as + ((wm * 64 + mi * 32 + r) * 72 + ks * 16 + 8 * h) * 2);
; #pragma unroll
;       for (int ni = 0; ni < 2; ++ni) bfr[ni] = *(const bf16x8*)(bs + ((wn * 64 + ni * 32 + r) * 72 + ks * 16 + 8 * h) * 2);
; #pragma unroll
;       for (int mi = 0; mi < 2; ++mi)
; #pragma unroll
;         for (int ni = 0; ni < 2; ++ni) {
;           if (SWAP) acc[mi][ni] = MFMA32(bfr[ni], af[mi], acc[mi][ni]);
;           else acc[mi][ni] = MFMA32(af[mi], bfr[ni], acc[mi][ni]);
;         }
;     }
;   };
;   gload(0, ra0, rb0);
;   lstore(0, ra0, rb0);
;   gload(1, ra1, rb1);
;   __syncthreads();
;   for (int kt = 0; kt < nk; kt += 2) {
;     if (kt + 2 < nk) gload(kt + 2, ra0, rb0);
;     compute(0);
;     lstore(1, ra1, rb1);
;     __syncthreads();
;     if (kt + 3 < nk) gload(kt + 3, ra1, rb1);
;     compute(1);
;     if (kt + 2 < nk) lstore(0, ra0, rb0);
;     __syncthreads();
	ds_read_b128 v[132:135], v210 offset:32768
	ds_read_b128 v[136:139], v210 offset:36864
	ds_read_b128 v[140:143], v214 offset:32768
	ds_read_b128 v[144:147], v214 offset:36864
	ds_read_b128 v[148:151], v214 offset:49152
	ds_read_b128 v[158:161], v214 offset:53248
	s_mov_b32 m0, s44
	s_nop 0
	global_load_lds_dwordx4 v208, s[68:69]
	global_load_lds_dwordx4 v209, s[70:71] offset:1024
	global_load_lds_dwordx4 v208, s[72:73] offset:2048
	global_load_lds_dwordx4 v209, s[74:75] offset:3072
	ds_read_b128 v[162:165], v211 offset:32768
	ds_read_b128 v[168:171], v211 offset:36864
	ds_read_b128 v[172:175], v215 offset:32768
	ds_read_b128 v[176:179], v215 offset:36864
	ds_read_b128 v[180:183], v215 offset:49152
	ds_read_b128 v[184:187], v215 offset:53248
	s_waitcnt lgkmcnt(6)
	v_mfma_f32_32x32x16_bf16 v[4:19], v[140:143], v[132:135], v[4:19]
	v_mfma_f32_32x32x16_bf16 v[68:83], v[140:143], v[136:139], v[68:83]
	v_mfma_f32_32x32x16_bf16 v[20:35], v[144:147], v[132:135], v[20:35]
	v_mfma_f32_32x32x16_bf16 v[84:99], v[144:147], v[136:139], v[84:99]
	v_mfma_f32_32x32x16_bf16 v[36:51], v[148:151], v[132:135], v[36:51]
	v_mfma_f32_32x32x16_bf16 v[100:115], v[148:151], v[136:139], v[100:115]
	v_mfma_f32_32x32x16_bf16 v[52:67], v[158:161], v[132:135], v[52:67]
	v_mfma_f32_32x32x16_bf16 v[116:131], v[158:161], v[136:139], v[116:131]
	s_mov_b32 m0, s46
	s_nop 0
	global_load_lds_dwordx4 v208, s[76:77]
	global_load_lds_dwordx4 v209, s[78:79] offset:1024
	global_load_lds_dwordx4 v208, s[80:81] offset:2048
	global_load_lds_dwordx4 v209, s[82:83] offset:3072
	v_add_u32_e32 v208, 0x80, v208
	v_add_u32_e32 v209, 0x80, v209
	ds_read_b128 v[132:135], v212 offset:32768
	ds_read_b128 v[136:139], v212 offset:36864
	ds_read_b128 v[140:143], v216 offset:32768
	ds_read_b128 v[144:147], v216 offset:36864
	ds_read_b128 v[148:151], v216 offset:49152
	ds_read_b128 v[158:161], v216 offset:53248
	s_waitcnt lgkmcnt(6)
	v_mfma_f32_32x32x16_bf16 v[4:19], v[172:175], v[162:165], v[4:19]
	v_mfma_f32_32x32x16_bf16 v[68:83], v[172:175], v[168:171], v[68:83]
	v_mfma_f32_32x32x16_bf16 v[20:35], v[176:179], v[162:165], v[20:35]
	v_mfma_f32_32x32x16_bf16 v[84:99], v[176:179], v[168:171], v[84:99]
	v_mfma_f32_32x32x16_bf16 v[36:51], v[180:183], v[162:165], v[36:51]
	v_mfma_f32_32x32x16_bf16 v[100:115], v[180:183], v[168:171], v[100:115]
	v_mfma_f32_32x32x16_bf16 v[52:67], v[184:187], v[162:165], v[52:67]
	v_mfma_f32_32x32x16_bf16 v[116:131], v[184:187], v[168:171], v[116:131]
	ds_read_b128 v[162:165], v213 offset:32768
	ds_read_b128 v[168:171], v213 offset:36864
	ds_read_b128 v[172:175], v217 offset:32768
	ds_read_b128 v[176:179], v217 offset:36864
	ds_read_b128 v[180:183], v217 offset:49152
	ds_read_b128 v[184:187], v217 offset:53248
	s_waitcnt lgkmcnt(6)
	v_mfma_f32_32x32x16_bf16 v[4:19], v[140:143], v[132:135], v[4:19]
	v_mfma_f32_32x32x16_bf16 v[68:83], v[140:143], v[136:139], v[68:83]
	v_mfma_f32_32x32x16_bf16 v[20:35], v[144:147], v[132:135], v[20:35]
	v_mfma_f32_32x32x16_bf16 v[84:99], v[144:147], v[136:139], v[84:99]
	v_mfma_f32_32x32x16_bf16 v[36:51], v[148:151], v[132:135], v[36:51]
	v_mfma_f32_32x32x16_bf16 v[100:115], v[148:151], v[136:139], v[100:115]
	v_mfma_f32_32x32x16_bf16 v[52:67], v[158:161], v[132:135], v[52:67]
	v_mfma_f32_32x32x16_bf16 v[116:131], v[158:161], v[136:139], v[116:131]
	s_waitcnt lgkmcnt(0)
	v_mfma_f32_32x32x16_bf16 v[4:19], v[172:175], v[162:165], v[4:19]
	v_mfma_f32_32x32x16_bf16 v[68:83], v[172:175], v[168:171], v[68:83]
	v_mfma_f32_32x32x16_bf16 v[20:35], v[176:179], v[162:165], v[20:35]
	v_mfma_f32_32x32x16_bf16 v[84:99], v[176:179], v[168:171], v[84:99]
	v_mfma_f32_32x32x16_bf16 v[36:51], v[180:183], v[162:165], v[36:51]
	v_mfma_f32_32x32x16_bf16 v[100:115], v[180:183], v[168:171], v[100:115]
	v_mfma_f32_32x32x16_bf16 v[52:67], v[184:187], v[162:165], v[52:67]
	v_mfma_f32_32x32x16_bf16 v[116:131], v[184:187], v[168:171], v[116:131]
	s_waitcnt vmcnt(0) lgkmcnt(0)
	s_barrier
	ds_read_b128 v[132:135], v210 offset:0
	ds_read_b128 v[136:139], v210 offset:4096
	ds_read_b128 v[140:143], v214 offset:0
	ds_read_b128 v[144:147], v214 offset:4096
	ds_read_b128 v[148:151], v214 offset:16384
	ds_read_b128 v[158:161], v214 offset:20480
	s_mov_b32 m0, s45
	s_nop 0
	global_load_lds_dwordx4 v208, s[68:69]
	global_load_lds_dwordx4 v209, s[70:71] offset:1024
	global_load_lds_dwordx4 v208, s[72:73] offset:2048
	global_load_lds_dwordx4 v209, s[74:75] offset:3072
	ds_read_b128 v[162:165], v211 offset:0
	ds_read_b128 v[168:171], v211 offset:4096
	ds_read_b128 v[172:175], v215 offset:0
	ds_read_b128 v[176:179], v215 offset:4096
	ds_read_b128 v[180:183], v215 offset:16384
	ds_read_b128 v[184:187], v215 offset:20480
	s_waitcnt lgkmcnt(6)
	v_mfma_f32_32x32x16_bf16 v[4:19], v[140:143], v[132:135], v[4:19]
	v_mfma_f32_32x32x16_bf16 v[68:83], v[140:143], v[136:139], v[68:83]
	v_mfma_f32_32x32x16_bf16 v[20:35], v[144:147], v[132:135], v[20:35]
	v_mfma_f32_32x32x16_bf16 v[84:99], v[144:147], v[136:139], v[84:99]
	v_mfma_f32_32x32x16_bf16 v[36:51], v[148:151], v[132:135], v[36:51]
	v_mfma_f32_32x32x16_bf16 v[100:115], v[148:151], v[136:139], v[100:115]
	v_mfma_f32_32x32x16_bf16 v[52:67], v[158:161], v[132:135], v[52:67]
	v_mfma_f32_32x32x16_bf16 v[116:131], v[158:161], v[136:139], v[116:131]
	s_mov_b32 m0, s47
	s_nop 0
	global_load_lds_dwordx4 v208, s[76:77]
	global_load_lds_dwordx4 v209, s[78:79] offset:1024
	global_load_lds_dwordx4 v208, s[80:81] offset:2048
	global_load_lds_dwordx4 v209, s[82:83] offset:3072
	v_add_u32_e32 v208, 0x80, v208
	v_add_u32_e32 v209, 0x80, v209
	ds_read_b128 v[132:135], v212 offset:0
	ds_read_b128 v[136:139], v212 offset:4096
	ds_read_b128 v[140:143], v216 offset:0
	ds_read_b128 v[144:147], v216 offset:4096
	ds_read_b128 v[148:151], v216 offset:16384
	ds_read_b128 v[158:161], v216 offset:20480
	s_waitcnt lgkmcnt(6)
; #define MFMA32(a, b, c) __builtin_amdgcn_mfma_f32_32x32x16_bf16((a), (b), (c), 0, 0, 0)
; template <bool SWAP, class Epi>
; DI void gemm_tile(const u16* __restrict__ A, int lda, const u16* __restrict__ Bw, int ldb, int K, char* lds, Epi epi) {
;     ...
;   auto compute = [&](int st) {
;     const char* as = lds + st * GEMM_STAGE;
;     const char* bs = as + 36864;
; #pragma unroll
;     for (int ks = 0; ks < 4; ++ks) {
;       bf16x8 af[2], bfr[2];
; #pragma unroll
;       for (int mi = 0; mi < 2; ++mi) af[mi] = *(const bf16x8*)(as + ((wm * 64 + mi * 32 + r) * 72 + ks * 16 + 8 * h) * 2);
; #pragma unroll
;       for (int ni = 0; ni < 2; ++ni) bfr[ni] = *(const bf16x8*)(bs + ((wn * 64 + ni * 32 + r) * 72 + ks * 16 + 8 * h) * 2);
; #pragma unroll
;       for (int mi = 0; mi < 2; ++mi)
; #pragma unroll
;         for (int ni = 0; ni < 2; ++ni) {
;           if (SWAP) acc[mi][ni] = MFMA32(bfr[ni], af[mi], acc[mi][ni]);
;           else acc[mi][ni] = MFMA32(af[mi], bfr[ni], acc[mi][ni]);
;         }
;     }
;   };
;   gload(0, ra0, rb0);
;   lstore(0, ra0, rb0);
;   gload(1, ra1, rb1);
;   __syncthreads();
;   for (int kt = 0; kt < nk; kt += 2) {
;     if (kt + 2 < nk) gload(kt + 2, ra0, rb0);
;     compute(0);
;     lstore(1, ra1, rb1);
;     __syncthreads();
;     if (kt + 3 < nk) gload(kt + 3, ra1, rb1);
;     compute(1);
;     if (kt + 2 < nk) lstore(0, ra0, rb0);
;     __syncthreads();
	v_mfma_f32_32x32x16_bf16 v[4:19], v[172:175], v[162:165], v[4:19]
	v_mfma_f32_32x32x16_bf16 v[68:83], v[172:175], v[168:171], v[68:83]
	v_mfma_f32_32x32x16_bf16 v[20:35], v[176:179], v[162:165], v[20:35]
	v_mfma_f32_32x32x16_bf16 v[84:99], v[176:179], v[168:171], v[84:99]
	v_mfma_f32_32x32x16_bf16 v[36:51], v[180:183], v[162:165], v[36:51]
	v_mfma_f32_32x32x16_bf16 v[100:115], v[180:183], v[168:171], v[100:115]
	v_mfma_f32_32x32x16_bf16 v[52:67], v[184:187], v[162:165], v[52:67]
	v_mfma_f32_32x32x16_bf16 v[116:131], v[184:187], v[168:171], v[116:131]
	ds_read_b128 v[162:165], v213 offset:0
	ds_read_b128 v[168:171], v213 offset:4096
	ds_read_b128 v[172:175], v217 offset:0
	ds_read_b128 v[176:179], v217 offset:4096
	ds_read_b128 v[180:183], v217 offset:16384
	ds_read_b128 v[184:187], v217 offset:20480
	s_waitcnt lgkmcnt(6)
	v_mfma_f32_32x32x16_bf16 v[4:19], v[140:143], v[132:135], v[4:19]
	v_mfma_f32_32x32x16_bf16 v[68:83], v[140:143], v[136:139], v[68:83]
	v_mfma_f32_32x32x16_bf16 v[20:35], v[144:147], v[132:135], v[20:35]
	v_mfma_f32_32x32x16_bf16 v[84:99], v[144:147], v[136:139], v[84:99]
	v_mfma_f32_32x32x16_bf16 v[36:51], v[148:151], v[132:135], v[36:51]
	v_mfma_f32_32x32x16_bf16 v[100:115], v[148:151], v[136:139], v[100:115]
	v_mfma_f32_32x32x16_bf16 v[52:67], v[158:161], v[132:135], v[52:67]
	v_mfma_f32_32x32x16_bf16 v[116:131], v[158:161], v[136:139], v[116:131]
	s_waitcnt lgkmcnt(0)
	v_mfma_f32_32x32x16_bf16 v[4:19], v[172:175], v[162:165], v[4:19]
	v_mfma_f32_32x32x16_bf16 v[68:83], v[172:175], v[168:171], v[68:83]
	v_mfma_f32_32x32x16_bf16 v[20:35], v[176:179], v[162:165], v[20:35]
	v_mfma_f32_32x32x16_bf16 v[84:99], v[176:179], v[168:171], v[84:99]
	v_mfma_f32_32x32x16_bf16 v[36:51], v[180:183], v[162:165], v[36:51]
	v_mfma_f32_32x32x16_bf16 v[100:115], v[180:183], v[168:171], v[100:115]
	v_mfma_f32_32x32x16_bf16 v[52:67], v[184:187], v[162:165], v[52:67]
	v_mfma_f32_32x32x16_bf16 v[116:131], v[184:187], v[168:171], v[116:131]
	s_waitcnt vmcnt(0) lgkmcnt(0)
	s_barrier
	ds_read_b128 v[132:135], v210 offset:32768
	ds_read_b128 v[136:139], v210 offset:36864
	ds_read_b128 v[140:143], v214 offset:32768
	ds_read_b128 v[144:147], v214 offset:36864
	ds_read_b128 v[148:151], v214 offset:49152
	ds_read_b128 v[158:161], v214 offset:53248
	s_mov_b32 m0, s44
	s_nop 0
	global_load_lds_dwordx4 v208, s[68:69]
	global_load_lds_dwordx4 v209, s[70:71] offset:1024
	global_load_lds_dwordx4 v208, s[72:73] offset:2048
	global_load_lds_dwordx4 v209, s[74:75] offset:3072
	ds_read_b128 v[162:165], v211 offset:32768
	ds_read_b128 v[168:171], v211 offset:36864
	ds_read_b128 v[172:175], v215 offset:32768
	ds_read_b128 v[176:179], v215 offset:36864
	ds_read_b128 v[180:183], v215 offset:49152
	ds_read_b128 v[184:187], v215 offset:53248
	s_waitcnt lgkmcnt(6)
	v_mfma_f32_32x32x16_bf16 v[4:19], v[140:143], v[132:135], v[4:19]
	v_mfma_f32_32x32x16_bf16 v[68:83], v[140:143], v[136:139], v[68:83]
	v_mfma_f32_32x32x16_bf16 v[20:35], v[144:147], v[132:135], v[20:35]
	v_mfma_f32_32x32x16_bf16 v[84:99], v[144:147], v[136:139], v[84:99]
	v_mfma_f32_32x32x16_bf16 v[36:51], v[148:151], v[132:135], v[36:51]
	v_mfma_f32_32x32x16_bf16 v[100:115], v[148:151], v[136:139], v[100:115]
	v_mfma_f32_32x32x16_bf16 v[52:67], v[158:161], v[132:135], v[52:67]
	v_mfma_f32_32x32x16_bf16 v[116:131], v[158:161], v[136:139], v[116:131]
	s_mov_b32 m0, s46
	s_nop 0
	global_load_lds_dwordx4 v208, s[76:77]
	global_load_lds_dwordx4 v209, s[78:79] offset:1024
	global_load_lds_dwordx4 v208, s[80:81] offset:2048
	global_load_lds_dwordx4 v209, s[82:83] offset:3072
	v_add_u32_e32 v208, 0x80, v208
	v_add_u32_e32 v209, 0x80, v209
	ds_read_b128 v[132:135], v212 offset:32768
	ds_read_b128 v[136:139], v212 offset:36864
	ds_read_b128 v[140:143], v216 offset:32768
	ds_read_b128 v[144:147], v216 offset:36864
	ds_read_b128 v[148:151], v216 offset:49152
	ds_read_b128 v[158:161], v216 offset:53248
	s_waitcnt lgkmcnt(6)
	v_mfma_f32_32x32x16_bf16 v[4:19], v[172:175], v[162:165], v[4:19]
	v_mfma_f32_32x32x16_bf16 v[68:83], v[172:175], v[168:171], v[68:83]
	v_mfma_f32_32x32x16_bf16 v[20:35], v[176:179], v[162:165], v[20:35]
	v_mfma_f32_32x32x16_bf16 v[84:99], v[176:179], v[168:171], v[84:99]
	v_mfma_f32_32x32x16_bf16 v[36:51], v[180:183], v[162:165], v[36:51]
	v_mfma_f32_32x32x16_bf16 v[100:115], v[180:183], v[168:171], v[100:115]
	v_mfma_f32_32x32x16_bf16 v[52:67], v[184:187], v[162:165], v[52:67]
	v_mfma_f32_32x32x16_bf16 v[116:131], v[184:187], v[168:171], v[116:131]
	ds_read_b128 v[162:165], v213 offset:32768
	ds_read_b128 v[168:171], v213 offset:36864
	ds_read_b128 v[172:175], v217 offset:32768
	ds_read_b128 v[176:179], v217 offset:36864
	ds_read_b128 v[180:183], v217 offset:49152
	ds_read_b128 v[184:187], v217 offset:53248
	s_waitcnt lgkmcnt(6)
	v_mfma_f32_32x32x16_bf16 v[4:19], v[140:143], v[132:135], v[4:19]
	v_mfma_f32_32x32x16_bf16 v[68:83], v[140:143], v[136:139], v[68:83]
	v_mfma_f32_32x32x16_bf16 v[20:35], v[144:147], v[132:135], v[20:35]
	v_mfma_f32_32x32x16_bf16 v[84:99], v[144:147], v[136:139], v[84:99]
	v_mfma_f32_32x32x16_bf16 v[36:51], v[148:151], v[132:135], v[36:51]
	v_mfma_f32_32x32x16_bf16 v[100:115], v[148:151], v[136:139], v[100:115]
	v_mfma_f32_32x32x16_bf16 v[52:67], v[158:161], v[132:135], v[52:67]
	v_mfma_f32_32x32x16_bf16 v[116:131], v[158:161], v[136:139], v[116:131]
	s_waitcnt lgkmcnt(0)
	v_mfma_f32_32x32x16_bf16 v[4:19], v[172:175], v[162:165], v[4:19]
	v_mfma_f32_32x32x16_bf16 v[68:83], v[172:175], v[168:171], v[68:83]
	v_mfma_f32_32x32x16_bf16 v[20:35], v[176:179], v[162:165], v[20:35]
	v_mfma_f32_32x32x16_bf16 v[84:99], v[176:179], v[168:171], v[84:99]
	v_mfma_f32_32x32x16_bf16 v[36:51], v[180:183], v[162:165], v[36:51]
	v_mfma_f32_32x32x16_bf16 v[100:115], v[180:183], v[168:171], v[100:115]
	v_mfma_f32_32x32x16_bf16 v[52:67], v[184:187], v[162:165], v[52:67]
	v_mfma_f32_32x32x16_bf16 v[116:131], v[184:187], v[168:171], v[116:131]
	s_waitcnt vmcnt(0) lgkmcnt(0)
	s_barrier
; #define MFMA32(a, b, c) __builtin_amdgcn_mfma_f32_32x32x16_bf16((a), (b), (c), 0, 0, 0)
; template <bool SWAP, class Epi>
; DI void gemm_tile(const u16* __restrict__ A, int lda, const u16* __restrict__ Bw, int ldb, int K, char* lds, Epi epi) {
;     ...
;   auto compute = [&](int st) {
;     const char* as = lds + st * GEMM_STAGE;
;     const char* bs = as + 36864;
; #pragma unroll
;     for (int ks = 0; ks < 4; ++ks) {
;       bf16x8 af[2], bfr[2];
; #pragma unroll
;       for (int mi = 0; mi < 2; ++mi) af[mi] = *(const bf16x8*)(as + ((wm * 64 + mi * 32 + r) * 72 + ks * 16 + 8 * h) * 2);
; #pragma unroll
;       for (int ni = 0; ni < 2; ++ni) bfr[ni] = *(const bf16x8*)(bs + ((wn * 64 + ni * 32 + r) * 72 + ks * 16 + 8 * h) * 2);
; #pragma unroll
;       for (int mi = 0; mi < 2; ++mi)
; #pragma unroll
;         for (int ni = 0; ni < 2; ++ni) {
;           if (SWAP) acc[mi][ni] = MFMA32(bfr[ni], af[mi], acc[mi][ni]);
;           else acc[mi][ni] = MFMA32(af[mi], bfr[ni], acc[mi][ni]);
;         }
;     }
;   };
;   gload(0, ra0, rb0);
;   lstore(0, ra0, rb0);
;   gload(1, ra1, rb1);
;   __syncthreads();
;   for (int kt = 0; kt < nk; kt += 2) {
;     if (kt + 2 < nk) gload(kt + 2, ra0, rb0);
;     compute(0);
;     lstore(1, ra1, rb1);
;     __syncthreads();
;     if (kt + 3 < nk) gload(kt + 3, ra1, rb1);
;     compute(1);
;     if (kt + 2 < nk) lstore(0, ra0, rb0);
;     __syncthreads();
	ds_read_b128 v[132:135], v210 offset:0
	ds_read_b128 v[136:139], v210 offset:4096
	ds_read_b128 v[140:143], v214 offset:0
	ds_read_b128 v[144:147], v214 offset:4096
	ds_read_b128 v[148:151], v214 offset:16384
	ds_read_b128 v[158:161], v214 offset:20480
	s_mov_b32 m0, s45
	s_nop 0
	global_load_lds_dwordx4 v208, s[68:69]
	global_load_lds_dwordx4 v209, s[70:71] offset:1024
	global_load_lds_dwordx4 v208, s[72:73] offset:2048
	global_load_lds_dwordx4 v209, s[74:75] offset:3072
	ds_read_b128 v[162:165], v211 offset:0
	ds_read_b128 v[168:171], v211 offset:4096
	ds_read_b128 v[172:175], v215 offset:0
	ds_read_b128 v[176:179], v215 offset:4096
	ds_read_b128 v[180:183], v215 offset:16384
	ds_read_b128 v[184:187], v215 offset:20480
	s_waitcnt lgkmcnt(6)
	v_mfma_f32_32x32x16_bf16 v[4:19], v[140:143], v[132:135], v[4:19]
	v_mfma_f32_32x32x16_bf16 v[68:83], v[140:143], v[136:139], v[68:83]
	v_mfma_f32_32x32x16_bf16 v[20:35], v[144:147], v[132:135], v[20:35]
	v_mfma_f32_32x32x16_bf16 v[84:99], v[144:147], v[136:139], v[84:99]
	v_mfma_f32_32x32x16_bf16 v[36:51], v[148:151], v[132:135], v[36:51]
	v_mfma_f32_32x32x16_bf16 v[100:115], v[148:151], v[136:139], v[100:115]
	v_mfma_f32_32x32x16_bf16 v[52:67], v[158:161], v[132:135], v[52:67]
	v_mfma_f32_32x32x16_bf16 v[116:131], v[158:161], v[136:139], v[116:131]
	s_mov_b32 m0, s47
	s_nop 0
	global_load_lds_dwordx4 v208, s[76:77]
	global_load_lds_dwordx4 v209, s[78:79] offset:1024
	global_load_lds_dwordx4 v208, s[80:81] offset:2048
	global_load_lds_dwordx4 v209, s[82:83] offset:3072
	v_add_u32_e32 v208, 0x80, v208
	v_add_u32_e32 v209, 0x80, v209
	ds_read_b128 v[132:135], v212 offset:0
	ds_read_b128 v[136:139], v212 offset:4096
	ds_read_b128 v[140:143], v216 offset:0
	ds_read_b128 v[144:147], v216 offset:4096
	ds_read_b128 v[148:151], v216 offset:16384
	ds_read_b128 v[158:161], v216 offset:20480
	s_waitcnt lgkmcnt(6)
	v_mfma_f32_32x32x16_bf16 v[4:19], v[172:175], v[162:165], v[4:19]
	v_mfma_f32_32x32x16_bf16 v[68:83], v[172:175], v[168:171], v[68:83]
	v_mfma_f32_32x32x16_bf16 v[20:35], v[176:179], v[162:165], v[20:35]
	v_mfma_f32_32x32x16_bf16 v[84:99], v[176:179], v[168:171], v[84:99]
	v_mfma_f32_32x32x16_bf16 v[36:51], v[180:183], v[162:165], v[36:51]
	v_mfma_f32_32x32x16_bf16 v[100:115], v[180:183], v[168:171], v[100:115]
	v_mfma_f32_32x32x16_bf16 v[52:67], v[184:187], v[162:165], v[52:67]
	v_mfma_f32_32x32x16_bf16 v[116:131], v[184:187], v[168:171], v[116:131]
	ds_read_b128 v[162:165], v213 offset:0
	ds_read_b128 v[168:171], v213 offset:4096
	ds_read_b128 v[172:175], v217 offset:0
	ds_read_b128 v[176:179], v217 offset:4096
	ds_read_b128 v[180:183], v217 offset:16384
	ds_read_b128 v[184:187], v217 offset:20480
	s_waitcnt lgkmcnt(6)
	v_mfma_f32_32x32x16_bf16 v[4:19], v[140:143], v[132:135], v[4:19]
	v_mfma_f32_32x32x16_bf16 v[68:83], v[140:143], v[136:139], v[68:83]
	v_mfma_f32_32x32x16_bf16 v[20:35], v[144:147], v[132:135], v[20:35]
	v_mfma_f32_32x32x16_bf16 v[84:99], v[144:147], v[136:139], v[84:99]
	v_mfma_f32_32x32x16_bf16 v[36:51], v[148:151], v[132:135], v[36:51]
	v_mfma_f32_32x32x16_bf16 v[100:115], v[148:151], v[136:139], v[100:115]
	v_mfma_f32_32x32x16_bf16 v[52:67], v[158:161], v[132:135], v[52:67]
	v_mfma_f32_32x32x16_bf16 v[116:131], v[158:161], v[136:139], v[116:131]
	s_waitcnt lgkmcnt(0)
	v_mfma_f32_32x32x16_bf16 v[4:19], v[172:175], v[162:165], v[4:19]
	v_mfma_f32_32x32x16_bf16 v[68:83], v[172:175], v[168:171], v[68:83]
	v_mfma_f32_32x32x16_bf16 v[20:35], v[176:179], v[162:165], v[20:35]
	v_mfma_f32_32x32x16_bf16 v[84:99], v[176:179], v[168:171], v[84:99]
	v_mfma_f32_32x32x16_bf16 v[36:51], v[180:183], v[162:165], v[36:51]
	v_mfma_f32_32x32x16_bf16 v[100:115], v[180:183], v[168:171], v[100:115]
	v_mfma_f32_32x32x16_bf16 v[52:67], v[184:187], v[162:165], v[52:67]
	v_mfma_f32_32x32x16_bf16 v[116:131], v[184:187], v[168:171], v[116:131]
	s_waitcnt vmcnt(0) lgkmcnt(0)
	s_barrier
	ds_read_b128 v[132:135], v210 offset:32768
	ds_read_b128 v[136:139], v210 offset:36864
	ds_read_b128 v[140:143], v214 offset:32768
	ds_read_b128 v[144:147], v214 offset:36864
	ds_read_b128 v[148:151], v214 offset:49152
	ds_read_b128 v[158:161], v214 offset:53248
	s_mov_b32 m0, s44
	s_nop 0
	global_load_lds_dwordx4 v208, s[68:69]
	global_load_lds_dwordx4 v209, s[70:71] offset:1024
	global_load_lds_dwordx4 v208, s[72:73] offset:2048
	global_load_lds_dwordx4 v209, s[74:75] offset:3072
	ds_read_b128 v[162:165], v211 offset:32768
	ds_read_b128 v[168:171], v211 offset:36864
	ds_read_b128 v[172:175], v215 offset:32768
	ds_read_b128 v[176:179], v215 offset:36864
	ds_read_b128 v[180:183], v215 offset:49152
	ds_read_b128 v[184:187], v215 offset:53248
	s_waitcnt lgkmcnt(6)
	v_mfma_f32_32x32x16_bf16 v[4:19], v[140:143], v[132:135], v[4:19]
	v_mfma_f32_32x32x16_bf16 v[68:83], v[140:143], v[136:139], v[68:83]
	v_mfma_f32_32x32x16_bf16 v[20:35], v[144:147], v[132:135], v[20:35]
	v_mfma_f32_32x32x16_bf16 v[84:99], v[144:147], v[136:139], v[84:99]
	v_mfma_f32_32x32x16_bf16 v[36:51], v[148:151], v[132:135], v[36:51]
	v_mfma_f32_32x32x16_bf16 v[100:115], v[148:151], v[136:139], v[100:115]
	v_mfma_f32_32x32x16_bf16 v[52:67], v[158:161], v[132:135], v[52:67]
	v_mfma_f32_32x32x16_bf16 v[116:131], v[158:161], v[136:139], v[116:131]
	s_mov_b32 m0, s46
	s_nop 0
	global_load_lds_dwordx4 v208, s[76:77]
	global_load_lds_dwordx4 v209, s[78:79] offset:1024
	global_load_lds_dwordx4 v208, s[80:81] offset:2048
	global_load_lds_dwordx4 v209, s[82:83] offset:3072
	v_add_u32_e32 v208, 0x80, v208
	v_add_u32_e32 v209, 0x80, v209
	ds_read_b128 v[132:135], v212 offset:32768
	ds_read_b128 v[136:139], v212 offset:36864
	ds_read_b128 v[140:143], v216 offset:32768
	ds_read_b128 v[144:147], v216 offset:36864
	ds_read_b128 v[148:151], v216 offset:49152
	ds_read_b128 v[158:161], v216 offset:53248
	s_waitcnt lgkmcnt(6)
; #define MFMA32(a, b, c) __builtin_amdgcn_mfma_f32_32x32x16_bf16((a), (b), (c), 0, 0, 0)
; template <bool SWAP, class Epi>
; DI void gemm_tile(const u16* __restrict__ A, int lda, const u16* __restrict__ Bw, int ldb, int K, char* lds, Epi epi) {
;     ...
;   auto compute = [&](int st) {
;     const char* as = lds + st * GEMM_STAGE;
;     const char* bs = as + 36864;
; #pragma unroll
;     for (int ks = 0; ks < 4; ++ks) {
;       bf16x8 af[2], bfr[2];
; #pragma unroll
;       for (int mi = 0; mi < 2; ++mi) af[mi] = *(const bf16x8*)(as + ((wm * 64 + mi * 32 + r) * 72 + ks * 16 + 8 * h) * 2);
; #pragma unroll
;       for (int ni = 0; ni < 2; ++ni) bfr[ni] = *(const bf16x8*)(bs + ((wn * 64 + ni * 32 + r) * 72 + ks * 16 + 8 * h) * 2);
; #pragma unroll
;       for (int mi = 0; mi < 2; ++mi)
; #pragma unroll
;         for (int ni = 0; ni < 2; ++ni) {
;           if (SWAP) acc[mi][ni] = MFMA32(bfr[ni], af[mi], acc[mi][ni]);
;           else acc[mi][ni] = MFMA32(af[mi], bfr[ni], acc[mi][ni]);
;         }
;     }
;   };
;   gload(0, ra0, rb0);
;   lstore(0, ra0, rb0);
;   gload(1, ra1, rb1);
;   __syncthreads();
;   for (int kt = 0; kt < nk; kt += 2) {
;     if (kt + 2 < nk) gload(kt + 2, ra0, rb0);
;     compute(0);
;     lstore(1, ra1, rb1);
;     __syncthreads();
;     if (kt + 3 < nk) gload(kt + 3, ra1, rb1);
;     compute(1);
;     if (kt + 2 < nk) lstore(0, ra0, rb0);
;     __syncthreads();
	v_mfma_f32_32x32x16_bf16 v[4:19], v[172:175], v[162:165], v[4:19]
	v_mfma_f32_32x32x16_bf16 v[68:83], v[172:175], v[168:171], v[68:83]
	v_mfma_f32_32x32x16_bf16 v[20:35], v[176:179], v[162:165], v[20:35]
	v_mfma_f32_32x32x16_bf16 v[84:99], v[176:179], v[168:171], v[84:99]
	v_mfma_f32_32x32x16_bf16 v[36:51], v[180:183], v[162:165], v[36:51]
	v_mfma_f32_32x32x16_bf16 v[100:115], v[180:183], v[168:171], v[100:115]
	v_mfma_f32_32x32x16_bf16 v[52:67], v[184:187], v[162:165], v[52:67]
	v_mfma_f32_32x32x16_bf16 v[116:131], v[184:187], v[168:171], v[116:131]
	ds_read_b128 v[162:165], v213 offset:32768
	ds_read_b128 v[168:171], v213 offset:36864
	ds_read_b128 v[172:175], v217 offset:32768
	ds_read_b128 v[176:179], v217 offset:36864
	ds_read_b128 v[180:183], v217 offset:49152
	ds_read_b128 v[184:187], v217 offset:53248
	s_waitcnt lgkmcnt(6)
	v_mfma_f32_32x32x16_bf16 v[4:19], v[140:143], v[132:135], v[4:19]
	v_mfma_f32_32x32x16_bf16 v[68:83], v[140:143], v[136:139], v[68:83]
	v_mfma_f32_32x32x16_bf16 v[20:35], v[144:147], v[132:135], v[20:35]
	v_mfma_f32_32x32x16_bf16 v[84:99], v[144:147], v[136:139], v[84:99]
	v_mfma_f32_32x32x16_bf16 v[36:51], v[148:151], v[132:135], v[36:51]
	v_mfma_f32_32x32x16_bf16 v[100:115], v[148:151], v[136:139], v[100:115]
	v_mfma_f32_32x32x16_bf16 v[52:67], v[158:161], v[132:135], v[52:67]
	v_mfma_f32_32x32x16_bf16 v[116:131], v[158:161], v[136:139], v[116:131]
	s_waitcnt lgkmcnt(0)
	v_mfma_f32_32x32x16_bf16 v[4:19], v[172:175], v[162:165], v[4:19]
	v_mfma_f32_32x32x16_bf16 v[68:83], v[172:175], v[168:171], v[68:83]
	v_mfma_f32_32x32x16_bf16 v[20:35], v[176:179], v[162:165], v[20:35]
	v_mfma_f32_32x32x16_bf16 v[84:99], v[176:179], v[168:171], v[84:99]
	v_mfma_f32_32x32x16_bf16 v[36:51], v[180:183], v[162:165], v[36:51]
	v_mfma_f32_32x32x16_bf16 v[100:115], v[180:183], v[168:171], v[100:115]
	v_mfma_f32_32x32x16_bf16 v[52:67], v[184:187], v[162:165], v[52:67]
	v_mfma_f32_32x32x16_bf16 v[116:131], v[184:187], v[168:171], v[116:131]
	s_waitcnt vmcnt(0) lgkmcnt(0)
	s_barrier
	ds_read_b128 v[132:135], v210 offset:0
	ds_read_b128 v[136:139], v210 offset:4096
	ds_read_b128 v[140:143], v214 offset:0
	ds_read_b128 v[144:147], v214 offset:4096
	ds_read_b128 v[148:151], v214 offset:16384
	ds_read_b128 v[158:161], v214 offset:20480
	s_mov_b32 m0, s45
	s_nop 0
	global_load_lds_dwordx4 v208, s[68:69]
	global_load_lds_dwordx4 v209, s[70:71] offset:1024
	global_load_lds_dwordx4 v208, s[72:73] offset:2048
	global_load_lds_dwordx4 v209, s[74:75] offset:3072
	ds_read_b128 v[162:165], v211 offset:0
	ds_read_b128 v[168:171], v211 offset:4096
	ds_read_b128 v[172:175], v215 offset:0
	ds_read_b128 v[176:179], v215 offset:4096
	ds_read_b128 v[180:183], v215 offset:16384
	ds_read_b128 v[184:187], v215 offset:20480
	s_waitcnt lgkmcnt(6)
	v_mfma_f32_32x32x16_bf16 v[4:19], v[140:143], v[132:135], v[4:19]
	v_mfma_f32_32x32x16_bf16 v[68:83], v[140:143], v[136:139], v[68:83]
	v_mfma_f32_32x32x16_bf16 v[20:35], v[144:147], v[132:135], v[20:35]
	v_mfma_f32_32x32x16_bf16 v[84:99], v[144:147], v[136:139], v[84:99]
	v_mfma_f32_32x32x16_bf16 v[36:51], v[148:151], v[132:135], v[36:51]
	v_mfma_f32_32x32x16_bf16 v[100:115], v[148:151], v[136:139], v[100:115]
	v_mfma_f32_32x32x16_bf16 v[52:67], v[158:161], v[132:135], v[52:67]
	v_mfma_f32_32x32x16_bf16 v[116:131], v[158:161], v[136:139], v[116:131]
	s_mov_b32 m0, s47
	s_nop 0
	global_load_lds_dwordx4 v208, s[76:77]
	global_load_lds_dwordx4 v209, s[78:79] offset:1024
	global_load_lds_dwordx4 v208, s[80:81] offset:2048
	global_load_lds_dwordx4 v209, s[82:83] offset:3072
	v_add_u32_e32 v208, 0x80, v208
	v_add_u32_e32 v209, 0x80, v209
	ds_read_b128 v[132:135], v212 offset:0
	ds_read_b128 v[136:139], v212 offset:4096
	ds_read_b128 v[140:143], v216 offset:0
	ds_read_b128 v[144:147], v216 offset:4096
	ds_read_b128 v[148:151], v216 offset:16384
	ds_read_b128 v[158:161], v216 offset:20480
	s_waitcnt lgkmcnt(6)
	v_mfma_f32_32x32x16_bf16 v[4:19], v[172:175], v[162:165], v[4:19]
	v_mfma_f32_32x32x16_bf16 v[68:83], v[172:175], v[168:171], v[68:83]
	v_mfma_f32_32x32x16_bf16 v[20:35], v[176:179], v[162:165], v[20:35]
	v_mfma_f32_32x32x16_bf16 v[84:99], v[176:179], v[168:171], v[84:99]
	v_mfma_f32_32x32x16_bf16 v[36:51], v[180:183], v[162:165], v[36:51]
	v_mfma_f32_32x32x16_bf16 v[100:115], v[180:183], v[168:171], v[100:115]
	v_mfma_f32_32x32x16_bf16 v[52:67], v[184:187], v[162:165], v[52:67]
	v_mfma_f32_32x32x16_bf16 v[116:131], v[184:187], v[168:171], v[116:131]
	ds_read_b128 v[162:165], v213 offset:0
	ds_read_b128 v[168:171], v213 offset:4096
	ds_read_b128 v[172:175], v217 offset:0
	ds_read_b128 v[176:179], v217 offset:4096
	ds_read_b128 v[180:183], v217 offset:16384
	ds_read_b128 v[184:187], v217 offset:20480
	s_waitcnt lgkmcnt(6)
	v_mfma_f32_32x32x16_bf16 v[4:19], v[140:143], v[132:135], v[4:19]
	v_mfma_f32_32x32x16_bf16 v[68:83], v[140:143], v[136:139], v[68:83]
	v_mfma_f32_32x32x16_bf16 v[20:35], v[144:147], v[132:135], v[20:35]
	v_mfma_f32_32x32x16_bf16 v[84:99], v[144:147], v[136:139], v[84:99]
	v_mfma_f32_32x32x16_bf16 v[36:51], v[148:151], v[132:135], v[36:51]
	v_mfma_f32_32x32x16_bf16 v[100:115], v[148:151], v[136:139], v[100:115]
	v_mfma_f32_32x32x16_bf16 v[52:67], v[158:161], v[132:135], v[52:67]
	v_mfma_f32_32x32x16_bf16 v[116:131], v[158:161], v[136:139], v[116:131]
	s_waitcnt lgkmcnt(0)
	v_mfma_f32_32x32x16_bf16 v[4:19], v[172:175], v[162:165], v[4:19]
	v_mfma_f32_32x32x16_bf16 v[68:83], v[172:175], v[168:171], v[68:83]
	v_mfma_f32_32x32x16_bf16 v[20:35], v[176:179], v[162:165], v[20:35]
	v_mfma_f32_32x32x16_bf16 v[84:99], v[176:179], v[168:171], v[84:99]
	v_mfma_f32_32x32x16_bf16 v[36:51], v[180:183], v[162:165], v[36:51]
	v_mfma_f32_32x32x16_bf16 v[100:115], v[180:183], v[168:171], v[100:115]
	v_mfma_f32_32x32x16_bf16 v[52:67], v[184:187], v[162:165], v[52:67]
	v_mfma_f32_32x32x16_bf16 v[116:131], v[184:187], v[168:171], v[116:131]
	s_waitcnt vmcnt(0) lgkmcnt(0)
	s_barrier
; #define MFMA32(a, b, c) __builtin_amdgcn_mfma_f32_32x32x16_bf16((a), (b), (c), 0, 0, 0)
; template <bool SWAP, class Epi>
; DI void gemm_tile(const u16* __restrict__ A, int lda, const u16* __restrict__ Bw, int ldb, int K, char* lds, Epi epi) {
;     ...
;   auto compute = [&](int st) {
;     const char* as = lds + st * GEMM_STAGE;
;     const char* bs = as + 36864;
; #pragma unroll
;     for (int ks = 0; ks < 4; ++ks) {
;       bf16x8 af[2], bfr[2];
; #pragma unroll
;       for (int mi = 0; mi < 2; ++mi) af[mi] = *(const bf16x8*)(as + ((wm * 64 + mi * 32 + r) * 72 + ks * 16 + 8 * h) * 2);
; #pragma unroll
;       for (int ni = 0; ni < 2; ++ni) bfr[ni] = *(const bf16x8*)(bs + ((wn * 64 + ni * 32 + r) * 72 + ks * 16 + 8 * h) * 2);
; #pragma unroll
;       for (int mi = 0; mi < 2; ++mi)
; #pragma unroll
;         for (int ni = 0; ni < 2; ++ni) {
;           if (SWAP) acc[mi][ni] = MFMA32(bfr[ni], af[mi], acc[mi][ni]);
;           else acc[mi][ni] = MFMA32(af[mi], bfr[ni], acc[mi][ni]);
;         }
;     }
;   };
;   gload(0, ra0, rb0);
;   lstore(0, ra0, rb0);
;   gload(1, ra1, rb1);
;   __syncthreads();
;   for (int kt = 0; kt < nk; kt += 2) {
;     if (kt + 2 < nk) gload(kt + 2, ra0, rb0);
;     compute(0);
;     lstore(1, ra1, rb1);
;     __syncthreads();
;     if (kt + 3 < nk) gload(kt + 3, ra1, rb1);
;     compute(1);
;     if (kt + 2 < nk) lstore(0, ra0, rb0);
;     __syncthreads();
	ds_read_b128 v[132:135], v210 offset:32768
	ds_read_b128 v[136:139], v210 offset:36864
	ds_read_b128 v[140:143], v214 offset:32768
	ds_read_b128 v[144:147], v214 offset:36864
	ds_read_b128 v[148:151], v214 offset:49152
	ds_read_b128 v[158:161], v214 offset:53248
	s_mov_b32 m0, s44
	s_nop 0
	global_load_lds_dwordx4 v208, s[68:69]
	global_load_lds_dwordx4 v209, s[70:71] offset:1024
	global_load_lds_dwordx4 v208, s[72:73] offset:2048
	global_load_lds_dwordx4 v209, s[74:75] offset:3072
	ds_read_b128 v[162:165], v211 offset:32768
	ds_read_b128 v[168:171], v211 offset:36864
	ds_read_b128 v[172:175], v215 offset:32768
	ds_read_b128 v[176:179], v215 offset:36864
	ds_read_b128 v[180:183], v215 offset:49152
	ds_read_b128 v[184:187], v215 offset:53248
	s_waitcnt lgkmcnt(6)
	v_mfma_f32_32x32x16_bf16 v[4:19], v[140:143], v[132:135], v[4:19]
	v_mfma_f32_32x32x16_bf16 v[68:83], v[140:143], v[136:139], v[68:83]
	v_mfma_f32_32x32x16_bf16 v[20:35], v[144:147], v[132:135], v[20:35]
	v_mfma_f32_32x32x16_bf16 v[84:99], v[144:147], v[136:139], v[84:99]
	v_mfma_f32_32x32x16_bf16 v[36:51], v[148:151], v[132:135], v[36:51]
	v_mfma_f32_32x32x16_bf16 v[100:115], v[148:151], v[136:139], v[100:115]
	v_mfma_f32_32x32x16_bf16 v[52:67], v[158:161], v[132:135], v[52:67]
	v_mfma_f32_32x32x16_bf16 v[116:131], v[158:161], v[136:139], v[116:131]
	s_mov_b32 m0, s46
	s_nop 0
	global_load_lds_dwordx4 v208, s[76:77]
	global_load_lds_dwordx4 v209, s[78:79] offset:1024
	global_load_lds_dwordx4 v208, s[80:81] offset:2048
	global_load_lds_dwordx4 v209, s[82:83] offset:3072
	v_add_u32_e32 v208, 0x80, v208
	v_add_u32_e32 v209, 0x80, v209
	ds_read_b128 v[132:135], v212 offset:32768
	ds_read_b128 v[136:139], v212 offset:36864
	ds_read_b128 v[140:143], v216 offset:32768
	ds_read_b128 v[144:147], v216 offset:36864
	ds_read_b128 v[148:151], v216 offset:49152
	ds_read_b128 v[158:161], v216 offset:53248
	s_waitcnt lgkmcnt(6)
	v_mfma_f32_32x32x16_bf16 v[4:19], v[172:175], v[162:165], v[4:19]
	v_mfma_f32_32x32x16_bf16 v[68:83], v[172:175], v[168:171], v[68:83]
	v_mfma_f32_32x32x16_bf16 v[20:35], v[176:179], v[162:165], v[20:35]
	v_mfma_f32_32x32x16_bf16 v[84:99], v[176:179], v[168:171], v[84:99]
	v_mfma_f32_32x32x16_bf16 v[36:51], v[180:183], v[162:165], v[36:51]
	v_mfma_f32_32x32x16_bf16 v[100:115], v[180:183], v[168:171], v[100:115]
	v_mfma_f32_32x32x16_bf16 v[52:67], v[184:187], v[162:165], v[52:67]
	v_mfma_f32_32x32x16_bf16 v[116:131], v[184:187], v[168:171], v[116:131]
	ds_read_b128 v[162:165], v213 offset:32768
	ds_read_b128 v[168:171], v213 offset:36864
	ds_read_b128 v[172:175], v217 offset:32768
	ds_read_b128 v[176:179], v217 offset:36864
	ds_read_b128 v[180:183], v217 offset:49152
	ds_read_b128 v[184:187], v217 offset:53248
	s_waitcnt lgkmcnt(6)
	v_mfma_f32_32x32x16_bf16 v[4:19], v[140:143], v[132:135], v[4:19]
	v_mfma_f32_32x32x16_bf16 v[68:83], v[140:143], v[136:139], v[68:83]
	v_mfma_f32_32x32x16_bf16 v[20:35], v[144:147], v[132:135], v[20:35]
	v_mfma_f32_32x32x16_bf16 v[84:99], v[144:147], v[136:139], v[84:99]
	v_mfma_f32_32x32x16_bf16 v[36:51], v[148:151], v[132:135], v[36:51]
	v_mfma_f32_32x32x16_bf16 v[100:115], v[148:151], v[136:139], v[100:115]
	v_mfma_f32_32x32x16_bf16 v[52:67], v[158:161], v[132:135], v[52:67]
	v_mfma_f32_32x32x16_bf16 v[116:131], v[158:161], v[136:139], v[116:131]
	s_waitcnt lgkmcnt(0)
	v_mfma_f32_32x32x16_bf16 v[4:19], v[172:175], v[162:165], v[4:19]
	v_mfma_f32_32x32x16_bf16 v[68:83], v[172:175], v[168:171], v[68:83]
	v_mfma_f32_32x32x16_bf16 v[20:35], v[176:179], v[162:165], v[20:35]
	v_mfma_f32_32x32x16_bf16 v[84:99], v[176:179], v[168:171], v[84:99]
	v_mfma_f32_32x32x16_bf16 v[36:51], v[180:183], v[162:165], v[36:51]
	v_mfma_f32_32x32x16_bf16 v[100:115], v[180:183], v[168:171], v[100:115]
	v_mfma_f32_32x32x16_bf16 v[52:67], v[184:187], v[162:165], v[52:67]
	v_mfma_f32_32x32x16_bf16 v[116:131], v[184:187], v[168:171], v[116:131]
	s_waitcnt vmcnt(0) lgkmcnt(0)
	s_barrier
	ds_read_b128 v[132:135], v210 offset:0
	ds_read_b128 v[136:139], v210 offset:4096
	ds_read_b128 v[140:143], v214 offset:0
	ds_read_b128 v[144:147], v214 offset:4096
	ds_read_b128 v[148:151], v214 offset:16384
	ds_read_b128 v[158:161], v214 offset:20480
	s_mov_b32 m0, s45
	s_nop 0
	global_load_lds_dwordx4 v208, s[68:69]
	global_load_lds_dwordx4 v209, s[70:71] offset:1024
	global_load_lds_dwordx4 v208, s[72:73] offset:2048
	global_load_lds_dwordx4 v209, s[74:75] offset:3072
	ds_read_b128 v[162:165], v211 offset:0
	ds_read_b128 v[168:171], v211 offset:4096
	ds_read_b128 v[172:175], v215 offset:0
	ds_read_b128 v[176:179], v215 offset:4096
	ds_read_b128 v[180:183], v215 offset:16384
	ds_read_b128 v[184:187], v215 offset:20480
	s_waitcnt lgkmcnt(6)
	v_mfma_f32_32x32x16_bf16 v[4:19], v[140:143], v[132:135], v[4:19]
	v_mfma_f32_32x32x16_bf16 v[68:83], v[140:143], v[136:139], v[68:83]
	v_mfma_f32_32x32x16_bf16 v[20:35], v[144:147], v[132:135], v[20:35]
	v_mfma_f32_32x32x16_bf16 v[84:99], v[144:147], v[136:139], v[84:99]
	v_mfma_f32_32x32x16_bf16 v[36:51], v[148:151], v[132:135], v[36:51]
	v_mfma_f32_32x32x16_bf16 v[100:115], v[148:151], v[136:139], v[100:115]
	v_mfma_f32_32x32x16_bf16 v[52:67], v[158:161], v[132:135], v[52:67]
	v_mfma_f32_32x32x16_bf16 v[116:131], v[158:161], v[136:139], v[116:131]
	s_mov_b32 m0, s47
	s_nop 0
	global_load_lds_dwordx4 v208, s[76:77]
	global_load_lds_dwordx4 v209, s[78:79] offset:1024
	global_load_lds_dwordx4 v208, s[80:81] offset:2048
	global_load_lds_dwordx4 v209, s[82:83] offset:3072
	v_add_u32_e32 v208, 0x80, v208
	v_add_u32_e32 v209, 0x80, v209
	ds_read_b128 v[132:135], v212 offset:0
	ds_read_b128 v[136:139], v212 offset:4096
	ds_read_b128 v[140:143], v216 offset:0
	ds_read_b128 v[144:147], v216 offset:4096
	ds_read_b128 v[148:151], v216 offset:16384
	ds_read_b128 v[158:161], v216 offset:20480
	s_waitcnt lgkmcnt(6)
; #define MFMA32(a, b, c) __builtin_amdgcn_mfma_f32_32x32x16_bf16((a), (b), (c), 0, 0, 0)
; template <bool SWAP, class Epi>
; DI void gemm_tile(const u16* __restrict__ A, int lda, const u16* __restrict__ Bw, int ldb, int K, char* lds, Epi epi) {
;     ...
;   auto compute = [&](int st) {
;     const char* as = lds + st * GEMM_STAGE;
;     const char* bs = as + 36864;
; #pragma unroll
;     for (int ks = 0; ks < 4; ++ks) {
;       bf16x8 af[2], bfr[2];
; #pragma unroll
;       for (int mi = 0; mi < 2; ++mi) af[mi] = *(const bf16x8*)(as + ((wm * 64 + mi * 32 + r) * 72 + ks * 16 + 8 * h) * 2);
; #pragma unroll
;       for (int ni = 0; ni < 2; ++ni) bfr[ni] = *(const bf16x8*)(bs + ((wn * 64 + ni * 32 + r) * 72 + ks * 16 + 8 * h) * 2);
; #pragma unroll
;       for (int mi = 0; mi < 2; ++mi)
; #pragma unroll
;         for (int ni = 0; ni < 2; ++ni) {
;           if (SWAP) acc[mi][ni] = MFMA32(bfr[ni], af[mi], acc[mi][ni]);
;           else acc[mi][ni] = MFMA32(af[mi], bfr[ni], acc[mi][ni]);
;         }
;     }
;   };
;   gload(0, ra0, rb0);
;   lstore(0, ra0, rb0);
;   gload(1, ra1, rb1);
;   __syncthreads();
;   for (int kt = 0; kt < nk; kt += 2) {
;     if (kt + 2 < nk) gload(kt + 2, ra0, rb0);
;     compute(0);
;     lstore(1, ra1, rb1);
;     __syncthreads();
;     if (kt + 3 < nk) gload(kt + 3, ra1, rb1);
;     compute(1);
;     if (kt + 2 < nk) lstore(0, ra0, rb0);
;     __syncthreads();
	v_mfma_f32_32x32x16_bf16 v[4:19], v[172:175], v[162:165], v[4:19]
	v_mfma_f32_32x32x16_bf16 v[68:83], v[172:175], v[168:171], v[68:83]
	v_mfma_f32_32x32x16_bf16 v[20:35], v[176:179], v[162:165], v[20:35]
	v_mfma_f32_32x32x16_bf16 v[84:99], v[176:179], v[168:171], v[84:99]
	v_mfma_f32_32x32x16_bf16 v[36:51], v[180:183], v[162:165], v[36:51]
	v_mfma_f32_32x32x16_bf16 v[100:115], v[180:183], v[168:171], v[100:115]
	v_mfma_f32_32x32x16_bf16 v[52:67], v[184:187], v[162:165], v[52:67]
	v_mfma_f32_32x32x16_bf16 v[116:131], v[184:187], v[168:171], v[116:131]
	ds_read_b128 v[162:165], v213 offset:0
	ds_read_b128 v[168:171], v213 offset:4096
	ds_read_b128 v[172:175], v217 offset:0
	ds_read_b128 v[176:179], v217 offset:4096
	ds_read_b128 v[180:183], v217 offset:16384
	ds_read_b128 v[184:187], v217 offset:20480
	s_waitcnt lgkmcnt(6)
	v_mfma_f32_32x32x16_bf16 v[4:19], v[140:143], v[132:135], v[4:19]
	v_mfma_f32_32x32x16_bf16 v[68:83], v[140:143], v[136:139], v[68:83]
	v_mfma_f32_32x32x16_bf16 v[20:35], v[144:147], v[132:135], v[20:35]
	v_mfma_f32_32x32x16_bf16 v[84:99], v[144:147], v[136:139], v[84:99]
	v_mfma_f32_32x32x16_bf16 v[36:51], v[148:151], v[132:135], v[36:51]
	v_mfma_f32_32x32x16_bf16 v[100:115], v[148:151], v[136:139], v[100:115]
	v_mfma_f32_32x32x16_bf16 v[52:67], v[158:161], v[132:135], v[52:67]
	v_mfma_f32_32x32x16_bf16 v[116:131], v[158:161], v[136:139], v[116:131]
	s_waitcnt lgkmcnt(0)
	v_mfma_f32_32x32x16_bf16 v[4:19], v[172:175], v[162:165], v[4:19]
	v_mfma_f32_32x32x16_bf16 v[68:83], v[172:175], v[168:171], v[68:83]
	v_mfma_f32_32x32x16_bf16 v[20:35], v[176:179], v[162:165], v[20:35]
	v_mfma_f32_32x32x16_bf16 v[84:99], v[176:179], v[168:171], v[84:99]
	v_mfma_f32_32x32x16_bf16 v[36:51], v[180:183], v[162:165], v[36:51]
	v_mfma_f32_32x32x16_bf16 v[100:115], v[180:183], v[168:171], v[100:115]
	v_mfma_f32_32x32x16_bf16 v[52:67], v[184:187], v[162:165], v[52:67]
	v_mfma_f32_32x32x16_bf16 v[116:131], v[184:187], v[168:171], v[116:131]
	s_waitcnt vmcnt(0) lgkmcnt(0)
	s_barrier
	ds_read_b128 v[132:135], v210 offset:32768
	ds_read_b128 v[136:139], v210 offset:36864
	ds_read_b128 v[140:143], v214 offset:32768
	ds_read_b128 v[144:147], v214 offset:36864
	ds_read_b128 v[148:151], v214 offset:49152
	ds_read_b128 v[158:161], v214 offset:53248
	s_mov_b32 m0, s44
	s_nop 0
	global_load_lds_dwordx4 v208, s[68:69]
	global_load_lds_dwordx4 v209, s[70:71] offset:1024
	global_load_lds_dwordx4 v208, s[72:73] offset:2048
	global_load_lds_dwordx4 v209, s[74:75] offset:3072
	ds_read_b128 v[162:165], v211 offset:32768
	ds_read_b128 v[168:171], v211 offset:36864
	ds_read_b128 v[172:175], v215 offset:32768
	ds_read_b128 v[176:179], v215 offset:36864
	ds_read_b128 v[180:183], v215 offset:49152
	ds_read_b128 v[184:187], v215 offset:53248
	s_waitcnt lgkmcnt(6)
	v_mfma_f32_32x32x16_bf16 v[4:19], v[140:143], v[132:135], v[4:19]
	v_mfma_f32_32x32x16_bf16 v[68:83], v[140:143], v[136:139], v[68:83]
	v_mfma_f32_32x32x16_bf16 v[20:35], v[144:147], v[132:135], v[20:35]
	v_mfma_f32_32x32x16_bf16 v[84:99], v[144:147], v[136:139], v[84:99]
	v_mfma_f32_32x32x16_bf16 v[36:51], v[148:151], v[132:135], v[36:51]
	v_mfma_f32_32x32x16_bf16 v[100:115], v[148:151], v[136:139], v[100:115]
	v_mfma_f32_32x32x16_bf16 v[52:67], v[158:161], v[132:135], v[52:67]
	v_mfma_f32_32x32x16_bf16 v[116:131], v[158:161], v[136:139], v[116:131]
	s_mov_b32 m0, s46
	s_nop 0
	global_load_lds_dwordx4 v208, s[76:77]
	global_load_lds_dwordx4 v209, s[78:79] offset:1024
	global_load_lds_dwordx4 v208, s[80:81] offset:2048
	global_load_lds_dwordx4 v209, s[82:83] offset:3072
	v_add_u32_e32 v208, 0x80, v208
	v_add_u32_e32 v209, 0x80, v209
	ds_read_b128 v[132:135], v212 offset:32768
	ds_read_b128 v[136:139], v212 offset:36864
	ds_read_b128 v[140:143], v216 offset:32768
	ds_read_b128 v[144:147], v216 offset:36864
	ds_read_b128 v[148:151], v216 offset:49152
	ds_read_b128 v[158:161], v216 offset:53248
	s_waitcnt lgkmcnt(6)
	v_mfma_f32_32x32x16_bf16 v[4:19], v[172:175], v[162:165], v[4:19]
	v_mfma_f32_32x32x16_bf16 v[68:83], v[172:175], v[168:171], v[68:83]
	v_mfma_f32_32x32x16_bf16 v[20:35], v[176:179], v[162:165], v[20:35]
	v_mfma_f32_32x32x16_bf16 v[84:99], v[176:179], v[168:171], v[84:99]
	v_mfma_f32_32x32x16_bf16 v[36:51], v[180:183], v[162:165], v[36:51]
	v_mfma_f32_32x32x16_bf16 v[100:115], v[180:183], v[168:171], v[100:115]
	v_mfma_f32_32x32x16_bf16 v[52:67], v[184:187], v[162:165], v[52:67]
	v_mfma_f32_32x32x16_bf16 v[116:131], v[184:187], v[168:171], v[116:131]
	ds_read_b128 v[162:165], v213 offset:32768
	ds_read_b128 v[168:171], v213 offset:36864
	ds_read_b128 v[172:175], v217 offset:32768
	ds_read_b128 v[176:179], v217 offset:36864
	ds_read_b128 v[180:183], v217 offset:49152
	ds_read_b128 v[184:187], v217 offset:53248
	s_waitcnt lgkmcnt(6)
	v_mfma_f32_32x32x16_bf16 v[4:19], v[140:143], v[132:135], v[4:19]
	v_mfma_f32_32x32x16_bf16 v[68:83], v[140:143], v[136:139], v[68:83]
	v_mfma_f32_32x32x16_bf16 v[20:35], v[144:147], v[132:135], v[20:35]
	v_mfma_f32_32x32x16_bf16 v[84:99], v[144:147], v[136:139], v[84:99]
	v_mfma_f32_32x32x16_bf16 v[36:51], v[148:151], v[132:135], v[36:51]
	v_mfma_f32_32x32x16_bf16 v[100:115], v[148:151], v[136:139], v[100:115]
	v_mfma_f32_32x32x16_bf16 v[52:67], v[158:161], v[132:135], v[52:67]
	v_mfma_f32_32x32x16_bf16 v[116:131], v[158:161], v[136:139], v[116:131]
	s_waitcnt lgkmcnt(0)
	v_mfma_f32_32x32x16_bf16 v[4:19], v[172:175], v[162:165], v[4:19]
	v_mfma_f32_32x32x16_bf16 v[68:83], v[172:175], v[168:171], v[68:83]
	v_mfma_f32_32x32x16_bf16 v[20:35], v[176:179], v[162:165], v[20:35]
	v_mfma_f32_32x32x16_bf16 v[84:99], v[176:179], v[168:171], v[84:99]
	v_mfma_f32_32x32x16_bf16 v[36:51], v[180:183], v[162:165], v[36:51]
	v_mfma_f32_32x32x16_bf16 v[100:115], v[180:183], v[168:171], v[100:115]
	v_mfma_f32_32x32x16_bf16 v[52:67], v[184:187], v[162:165], v[52:67]
	v_mfma_f32_32x32x16_bf16 v[116:131], v[184:187], v[168:171], v[116:131]
	s_waitcnt vmcnt(0) lgkmcnt(0)
	s_barrier
; #define MFMA32(a, b, c) __builtin_amdgcn_mfma_f32_32x32x16_bf16((a), (b), (c), 0, 0, 0)
; template <bool SWAP, class Epi>
; DI void gemm_tile(const u16* __restrict__ A, int lda, const u16* __restrict__ Bw, int ldb, int K, char* lds, Epi epi) {
;     ...
;   auto compute = [&](int st) {
;     const char* as = lds + st * GEMM_STAGE;
;     const char* bs = as + 36864;
; #pragma unroll
;     for (int ks = 0; ks < 4; ++ks) {
;       bf16x8 af[2], bfr[2];
; #pragma unroll
;       for (int mi = 0; mi < 2; ++mi) af[mi] = *(const bf16x8*)(as + ((wm * 64 + mi * 32 + r) * 72 + ks * 16 + 8 * h) * 2);
; #pragma unroll
;       for (int ni = 0; ni < 2; ++ni) bfr[ni] = *(const bf16x8*)(bs + ((wn * 64 + ni * 32 + r) * 72 + ks * 16 + 8 * h) * 2);
; #pragma unroll
;       for (int mi = 0; mi < 2; ++mi)
; #pragma unroll
;         for (int ni = 0; ni < 2; ++ni) {
;           if (SWAP) acc[mi][ni] = MFMA32(bfr[ni], af[mi], acc[mi][ni]);
;           else acc[mi][ni] = MFMA32(af[mi], bfr[ni], acc[mi][ni]);
;         }
;     }
;   };
;   gload(0, ra0, rb0);
;   lstore(0, ra0, rb0);
;   gload(1, ra1, rb1);
;   __syncthreads();
;   for (int kt = 0; kt < nk; kt += 2) {
;     if (kt + 2 < nk) gload(kt + 2, ra0, rb0);
;     compute(0);
;     lstore(1, ra1, rb1);
;     __syncthreads();
;     if (kt + 3 < nk) gload(kt + 3, ra1, rb1);
;     compute(1);
;     if (kt + 2 < nk) lstore(0, ra0, rb0);
;     __syncthreads();
	ds_read_b128 v[132:135], v210 offset:0
	ds_read_b128 v[136:139], v210 offset:4096
	ds_read_b128 v[140:143], v214 offset:0
	ds_read_b128 v[144:147], v214 offset:4096
	ds_read_b128 v[148:151], v214 offset:16384
	ds_read_b128 v[158:161], v214 offset:20480
	s_mov_b32 m0, s45
	s_nop 0
	global_load_lds_dwordx4 v208, s[68:69]
	global_load_lds_dwordx4 v209, s[70:71] offset:1024
	global_load_lds_dwordx4 v208, s[72:73] offset:2048
	global_load_lds_dwordx4 v209, s[74:75] offset:3072
	ds_read_b128 v[162:165], v211 offset:0
	ds_read_b128 v[168:171], v211 offset:4096
	ds_read_b128 v[172:175], v215 offset:0
	ds_read_b128 v[176:179], v215 offset:4096
	ds_read_b128 v[180:183], v215 offset:16384
	ds_read_b128 v[184:187], v215 offset:20480
	s_waitcnt lgkmcnt(6)
	v_mfma_f32_32x32x16_bf16 v[4:19], v[140:143], v[132:135], v[4:19]
	v_mfma_f32_32x32x16_bf16 v[68:83], v[140:143], v[136:139], v[68:83]
	v_mfma_f32_32x32x16_bf16 v[20:35], v[144:147], v[132:135], v[20:35]
	v_mfma_f32_32x32x16_bf16 v[84:99], v[144:147], v[136:139], v[84:99]
	v_mfma_f32_32x32x16_bf16 v[36:51], v[148:151], v[132:135], v[36:51]
	v_mfma_f32_32x32x16_bf16 v[100:115], v[148:151], v[136:139], v[100:115]
	v_mfma_f32_32x32x16_bf16 v[52:67], v[158:161], v[132:135], v[52:67]
	v_mfma_f32_32x32x16_bf16 v[116:131], v[158:161], v[136:139], v[116:131]
	s_mov_b32 m0, s47
	s_nop 0
	global_load_lds_dwordx4 v208, s[76:77]
	global_load_lds_dwordx4 v209, s[78:79] offset:1024
	global_load_lds_dwordx4 v208, s[80:81] offset:2048
	global_load_lds_dwordx4 v209, s[82:83] offset:3072
	v_add_u32_e32 v208, 0x80, v208
	v_add_u32_e32 v209, 0x80, v209
	ds_read_b128 v[132:135], v212 offset:0
	ds_read_b128 v[136:139], v212 offset:4096
	ds_read_b128 v[140:143], v216 offset:0
	ds_read_b128 v[144:147], v216 offset:4096
	ds_read_b128 v[148:151], v216 offset:16384
	ds_read_b128 v[158:161], v216 offset:20480
	s_waitcnt lgkmcnt(6)
	v_mfma_f32_32x32x16_bf16 v[4:19], v[172:175], v[162:165], v[4:19]
	v_mfma_f32_32x32x16_bf16 v[68:83], v[172:175], v[168:171], v[68:83]
	v_mfma_f32_32x32x16_bf16 v[20:35], v[176:179], v[162:165], v[20:35]
	v_mfma_f32_32x32x16_bf16 v[84:99], v[176:179], v[168:171], v[84:99]
	v_mfma_f32_32x32x16_bf16 v[36:51], v[180:183], v[162:165], v[36:51]
	v_mfma_f32_32x32x16_bf16 v[100:115], v[180:183], v[168:171], v[100:115]
	v_mfma_f32_32x32x16_bf16 v[52:67], v[184:187], v[162:165], v[52:67]
	v_mfma_f32_32x32x16_bf16 v[116:131], v[184:187], v[168:171], v[116:131]
	ds_read_b128 v[162:165], v213 offset:0
	ds_read_b128 v[168:171], v213 offset:4096
	ds_read_b128 v[172:175], v217 offset:0
	ds_read_b128 v[176:179], v217 offset:4096
	ds_read_b128 v[180:183], v217 offset:16384
	ds_read_b128 v[184:187], v217 offset:20480
	s_waitcnt lgkmcnt(6)
	v_mfma_f32_32x32x16_bf16 v[4:19], v[140:143], v[132:135], v[4:19]
	v_mfma_f32_32x32x16_bf16 v[68:83], v[140:143], v[136:139], v[68:83]
	v_mfma_f32_32x32x16_bf16 v[20:35], v[144:147], v[132:135], v[20:35]
	v_mfma_f32_32x32x16_bf16 v[84:99], v[144:147], v[136:139], v[84:99]
	v_mfma_f32_32x32x16_bf16 v[36:51], v[148:151], v[132:135], v[36:51]
	v_mfma_f32_32x32x16_bf16 v[100:115], v[148:151], v[136:139], v[100:115]
	v_mfma_f32_32x32x16_bf16 v[52:67], v[158:161], v[132:135], v[52:67]
	v_mfma_f32_32x32x16_bf16 v[116:131], v[158:161], v[136:139], v[116:131]
	s_waitcnt lgkmcnt(0)
	v_mfma_f32_32x32x16_bf16 v[4:19], v[172:175], v[162:165], v[4:19]
	v_mfma_f32_32x32x16_bf16 v[68:83], v[172:175], v[168:171], v[68:83]
	v_mfma_f32_32x32x16_bf16 v[20:35], v[176:179], v[162:165], v[20:35]
	v_mfma_f32_32x32x16_bf16 v[84:99], v[176:179], v[168:171], v[84:99]
	v_mfma_f32_32x32x16_bf16 v[36:51], v[180:183], v[162:165], v[36:51]
	v_mfma_f32_32x32x16_bf16 v[100:115], v[180:183], v[168:171], v[100:115]
	v_mfma_f32_32x32x16_bf16 v[52:67], v[184:187], v[162:165], v[52:67]
	v_mfma_f32_32x32x16_bf16 v[116:131], v[184:187], v[168:171], v[116:131]
	s_waitcnt vmcnt(0) lgkmcnt(0)
	s_barrier
	ds_read_b128 v[132:135], v210 offset:32768
	ds_read_b128 v[136:139], v210 offset:36864
	ds_read_b128 v[140:143], v214 offset:32768
	ds_read_b128 v[144:147], v214 offset:36864
	ds_read_b128 v[148:151], v214 offset:49152
	ds_read_b128 v[158:161], v214 offset:53248
	ds_read_b128 v[162:165], v211 offset:32768
	ds_read_b128 v[168:171], v211 offset:36864
	ds_read_b128 v[172:175], v215 offset:32768
	ds_read_b128 v[176:179], v215 offset:36864
	ds_read_b128 v[180:183], v215 offset:49152
	ds_read_b128 v[184:187], v215 offset:53248
	s_waitcnt lgkmcnt(6)
	v_mfma_f32_32x32x16_bf16 v[4:19], v[140:143], v[132:135], v[4:19]
	v_mfma_f32_32x32x16_bf16 v[68:83], v[140:143], v[136:139], v[68:83]
	v_mfma_f32_32x32x16_bf16 v[20:35], v[144:147], v[132:135], v[20:35]
	v_mfma_f32_32x32x16_bf16 v[84:99], v[144:147], v[136:139], v[84:99]
	v_mfma_f32_32x32x16_bf16 v[36:51], v[148:151], v[132:135], v[36:51]
	v_mfma_f32_32x32x16_bf16 v[100:115], v[148:151], v[136:139], v[100:115]
	v_mfma_f32_32x32x16_bf16 v[52:67], v[158:161], v[132:135], v[52:67]
	v_mfma_f32_32x32x16_bf16 v[116:131], v[158:161], v[136:139], v[116:131]
	ds_read_b128 v[132:135], v212 offset:32768
	ds_read_b128 v[136:139], v212 offset:36864
	ds_read_b128 v[140:143], v216 offset:32768
	ds_read_b128 v[144:147], v216 offset:36864
	ds_read_b128 v[148:151], v216 offset:49152
	ds_read_b128 v[158:161], v216 offset:53248
	s_waitcnt lgkmcnt(6)
; DI unsigned pk2(float a, float b) { f32x2 v = {a, b}; return __builtin_bit_cast(unsigned, __builtin_convertvector(v, bf2_t)); }
; DI void store_rowmajor(u16* dst, const f32x16& a, int h, float sc) {
; #pragma unroll
;   for (int kp = 0; kp < 2; ++kp) {
;     const int g = 2 * kp;
;     unsigned ax = pk2(a[4 * g] * sc, a[4 * g + 1] * sc), ay = pk2(a[4 * g + 2] * sc, a[4 * g + 3] * sc);
;     unsigned bx = pk2(a[4 * g + 4] * sc, a[4 * g + 5] * sc), by = pk2(a[4 * g + 6] * sc, a[4 * g + 7] * sc);
;     const u32x2 rx = __builtin_amdgcn_permlane32_swap(ax, bx, false, false);
;     const u32x2 ry = __builtin_amdgcn_permlane32_swap(ay, by, false, false);
;     const u32x4 v = {rx[0], ry[0], rx[1], ry[1]};
;     *(u32x4*)(dst + 8 * (g + h)) = v;
;   }
; }
; DI void inproj_tile(const Params& p, int l, int mt, int nt, char* lds) {
;     ...
;     gemm_tile<true>(A, DM, Bw, DM, DM, lds, [&](int mi, int ni, const f32x16& a) {
;       const int tok = m0 + wm * 64 + mi * 32 + r;
;       store_rowmajor(p.H + (size_t)tok * LDH + nt * 128 + wn * 64 + ni * 32, a, h, 1.f);
	v_mfma_f32_32x32x16_bf16 v[4:19], v[172:175], v[162:165], v[4:19]
	v_mfma_f32_32x32x16_bf16 v[68:83], v[172:175], v[168:171], v[68:83]
	v_mfma_f32_32x32x16_bf16 v[20:35], v[176:179], v[162:165], v[20:35]
	v_mfma_f32_32x32x16_bf16 v[84:99], v[176:179], v[168:171], v[84:99]
	v_mfma_f32_32x32x16_bf16 v[36:51], v[180:183], v[162:165], v[36:51]
	v_mfma_f32_32x32x16_bf16 v[100:115], v[180:183], v[168:171], v[100:115]
	v_mfma_f32_32x32x16_bf16 v[52:67], v[184:187], v[162:165], v[52:67]
	v_mfma_f32_32x32x16_bf16 v[116:131], v[184:187], v[168:171], v[116:131]
	ds_read_b128 v[162:165], v213 offset:32768
	ds_read_b128 v[168:171], v213 offset:36864
	ds_read_b128 v[172:175], v217 offset:32768
	ds_read_b128 v[176:179], v217 offset:36864
	ds_read_b128 v[180:183], v217 offset:49152
	ds_read_b128 v[184:187], v217 offset:53248
	s_waitcnt lgkmcnt(6)
	v_mfma_f32_32x32x16_bf16 v[4:19], v[140:143], v[132:135], v[4:19]
	v_mfma_f32_32x32x16_bf16 v[68:83], v[140:143], v[136:139], v[68:83]
	v_mfma_f32_32x32x16_bf16 v[20:35], v[144:147], v[132:135], v[20:35]
	v_mfma_f32_32x32x16_bf16 v[84:99], v[144:147], v[136:139], v[84:99]
	v_mfma_f32_32x32x16_bf16 v[36:51], v[148:151], v[132:135], v[36:51]
	v_mfma_f32_32x32x16_bf16 v[100:115], v[148:151], v[136:139], v[100:115]
	v_mfma_f32_32x32x16_bf16 v[52:67], v[158:161], v[132:135], v[52:67]
	v_mfma_f32_32x32x16_bf16 v[116:131], v[158:161], v[136:139], v[116:131]
	s_waitcnt lgkmcnt(0)
	v_mfma_f32_32x32x16_bf16 v[4:19], v[172:175], v[162:165], v[4:19]
	v_mfma_f32_32x32x16_bf16 v[68:83], v[172:175], v[168:171], v[68:83]
	v_mfma_f32_32x32x16_bf16 v[20:35], v[176:179], v[162:165], v[20:35]
	v_mfma_f32_32x32x16_bf16 v[84:99], v[176:179], v[168:171], v[84:99]
	v_mfma_f32_32x32x16_bf16 v[36:51], v[180:183], v[162:165], v[36:51]
	v_mfma_f32_32x32x16_bf16 v[100:115], v[180:183], v[168:171], v[100:115]
	v_mfma_f32_32x32x16_bf16 v[52:67], v[184:187], v[162:165], v[52:67]
	v_mfma_f32_32x32x16_bf16 v[116:131], v[184:187], v[168:171], v[116:131]
	s_waitcnt lgkmcnt(0)
	s_barrier
	s_nop 7
	s_nop 7
	v_cvt_pk_bf16_f32 v224, v4, v5
	v_cvt_pk_bf16_f32 v225, v6, v7
	v_cvt_pk_bf16_f32 v226, v8, v9
	v_cvt_pk_bf16_f32 v227, v10, v11
	s_nop 1
	v_permlane32_swap_b32_e32 v224, v226
	v_permlane32_swap_b32_e32 v225, v227
	s_nop 0
	global_store_dwordx4 v218, v[224:227], s[8:9]
	v_cvt_pk_bf16_f32 v228, v12, v13
	v_cvt_pk_bf16_f32 v229, v14, v15
	v_cvt_pk_bf16_f32 v230, v16, v17
	v_cvt_pk_bf16_f32 v231, v18, v19
	s_nop 1
	v_permlane32_swap_b32_e32 v228, v230
	v_permlane32_swap_b32_e32 v229, v231
	s_nop 0
	global_store_dwordx4 v218, v[228:231], s[8:9] offset:32
	v_cvt_pk_bf16_f32 v224, v68, v69
	v_cvt_pk_bf16_f32 v225, v70, v71
	v_cvt_pk_bf16_f32 v226, v72, v73
	v_cvt_pk_bf16_f32 v227, v74, v75
	s_nop 1
	v_permlane32_swap_b32_e32 v224, v226
	v_permlane32_swap_b32_e32 v225, v227
	s_nop 0
	global_store_dwordx4 v219, v[224:227], s[8:9]
	v_cvt_pk_bf16_f32 v228, v76, v77
	v_cvt_pk_bf16_f32 v229, v78, v79
	v_cvt_pk_bf16_f32 v230, v80, v81
	v_cvt_pk_bf16_f32 v231, v82, v83
	s_nop 1
	v_permlane32_swap_b32_e32 v228, v230
	v_permlane32_swap_b32_e32 v229, v231
	s_nop 0
	global_store_dwordx4 v219, v[228:231], s[8:9] offset:32
	v_cvt_pk_bf16_f32 v224, v20, v21
	v_cvt_pk_bf16_f32 v225, v22, v23
	v_cvt_pk_bf16_f32 v226, v24, v25
	v_cvt_pk_bf16_f32 v227, v26, v27
	s_nop 1
	v_permlane32_swap_b32_e32 v224, v226
	v_permlane32_swap_b32_e32 v225, v227
	s_nop 0
	global_store_dwordx4 v218, v[224:227], s[8:9] offset:64
	v_cvt_pk_bf16_f32 v228, v28, v29
	v_cvt_pk_bf16_f32 v229, v30, v31
	v_cvt_pk_bf16_f32 v230, v32, v33
	v_cvt_pk_bf16_f32 v231, v34, v35
	s_nop 1
	v_permlane32_swap_b32_e32 v228, v230
	v_permlane32_swap_b32_e32 v229, v231
	s_nop 0
	global_store_dwordx4 v218, v[228:231], s[8:9] offset:96
	v_cvt_pk_bf16_f32 v224, v84, v85
	v_cvt_pk_bf16_f32 v225, v86, v87
	v_cvt_pk_bf16_f32 v226, v88, v89
	v_cvt_pk_bf16_f32 v227, v90, v91
	s_nop 1
	v_permlane32_swap_b32_e32 v224, v226
	v_permlane32_swap_b32_e32 v225, v227
	s_nop 0
	global_store_dwordx4 v219, v[224:227], s[8:9] offset:64
	v_cvt_pk_bf16_f32 v228, v92, v93
	v_cvt_pk_bf16_f32 v229, v94, v95
	v_cvt_pk_bf16_f32 v230, v96, v97
	v_cvt_pk_bf16_f32 v231, v98, v99
	s_nop 1
	v_permlane32_swap_b32_e32 v228, v230
	v_permlane32_swap_b32_e32 v229, v231
	s_nop 0
	global_store_dwordx4 v219, v[228:231], s[8:9] offset:96
	v_cvt_pk_bf16_f32 v224, v36, v37
	v_cvt_pk_bf16_f32 v225, v38, v39
	v_cvt_pk_bf16_f32 v226, v40, v41
	v_cvt_pk_bf16_f32 v227, v42, v43
	s_nop 1
	v_permlane32_swap_b32_e32 v224, v226
	v_permlane32_swap_b32_e32 v225, v227
	s_nop 0
	global_store_dwordx4 v218, v[224:227], s[8:9] offset:256
	v_cvt_pk_bf16_f32 v228, v44, v45
	v_cvt_pk_bf16_f32 v229, v46, v47
	v_cvt_pk_bf16_f32 v230, v48, v49
	v_cvt_pk_bf16_f32 v231, v50, v51
	s_nop 1
	v_permlane32_swap_b32_e32 v228, v230
	v_permlane32_swap_b32_e32 v229, v231
	s_nop 0
	global_store_dwordx4 v218, v[228:231], s[8:9] offset:288
	v_cvt_pk_bf16_f32 v224, v100, v101
	v_cvt_pk_bf16_f32 v225, v102, v103
	v_cvt_pk_bf16_f32 v226, v104, v105
	v_cvt_pk_bf16_f32 v227, v106, v107
	s_nop 1
	v_permlane32_swap_b32_e32 v224, v226
	v_permlane32_swap_b32_e32 v225, v227
	s_nop 0
	global_store_dwordx4 v219, v[224:227], s[8:9] offset:256
	v_cvt_pk_bf16_f32 v228, v108, v109
	v_cvt_pk_bf16_f32 v229, v110, v111
	v_cvt_pk_bf16_f32 v230, v112, v113
	v_cvt_pk_bf16_f32 v231, v114, v115
	s_nop 1
	v_permlane32_swap_b32_e32 v228, v230
	v_permlane32_swap_b32_e32 v229, v231
	s_nop 0
	global_store_dwordx4 v219, v[228:231], s[8:9] offset:288
	v_cvt_pk_bf16_f32 v224, v52, v53
	v_cvt_pk_bf16_f32 v225, v54, v55
	v_cvt_pk_bf16_f32 v226, v56, v57
	v_cvt_pk_bf16_f32 v227, v58, v59
	s_nop 1
	v_permlane32_swap_b32_e32 v224, v226
	v_permlane32_swap_b32_e32 v225, v227
	s_nop 0
	global_store_dwordx4 v218, v[224:227], s[8:9] offset:320
	v_cvt_pk_bf16_f32 v228, v60, v61
	v_cvt_pk_bf16_f32 v229, v62, v63
	v_cvt_pk_bf16_f32 v230, v64, v65
	v_cvt_pk_bf16_f32 v231, v66, v67
	s_nop 1
	v_permlane32_swap_b32_e32 v228, v230
	v_permlane32_swap_b32_e32 v229, v231
	s_nop 0
	global_store_dwordx4 v218, v[228:231], s[8:9] offset:352
	v_cvt_pk_bf16_f32 v224, v116, v117
	v_cvt_pk_bf16_f32 v225, v118, v119
	v_cvt_pk_bf16_f32 v226, v120, v121
	v_cvt_pk_bf16_f32 v227, v122, v123
	s_nop 1
	v_permlane32_swap_b32_e32 v224, v226
	v_permlane32_swap_b32_e32 v225, v227
	s_nop 0
	global_store_dwordx4 v219, v[224:227], s[8:9] offset:320
	v_cvt_pk_bf16_f32 v228, v124, v125
	v_cvt_pk_bf16_f32 v229, v126, v127
	v_cvt_pk_bf16_f32 v230, v128, v129
	v_cvt_pk_bf16_f32 v231, v130, v131
	s_nop 1
	v_permlane32_swap_b32_e32 v228, v230
	v_permlane32_swap_b32_e32 v229, v231
	s_nop 0
	global_store_dwordx4 v219, v[228:231], s[8:9] offset:352
	s_branch .LBB0_323

; DI int opaque_tid() { int t = threadIdx.x; asm volatile("" : "+v"(t)); return t; }
; DI void inproj_tile(const Params& p, int l, int mt, int nt, char* lds) {
;   const int tid = opaque_tid(), lane = tid & 63, w = tid >> 6, r = lane & 31, h = lane >> 5;
;   const int wm = w & 3, wn = w >> 2;
;   const int m0 = mt * 256;
;   const u16* A = p.Xb + (size_t)m0 * DM;
;   const u16* Bw = p.Wt_in + (size_t)(l & 1) * NIN * DM + (size_t)nt * 128 * DM;
;   if (nt < 42) {
; __global__ void __launch_bounds__(NTHREADS) mega(Params p) {
;     ...
;       for (int j = blockIdx.x; j < 66 * 48; j += gridDim.x) inproj_tile(p, l, j / 48, j % 48, lds);
.LBB0_323:
	s_mov_b32 s25, s101
	v_readlane_b32 s0, v238, 18
	s_add_i32 s25, s25, 32
	s_add_i32 s24, s24, s0
	s_add_i32 s23, s23, s22
	v_readlane_b32 s0, v238, 16
	s_and_b32 s0, s0, 7
	s_movk_i32 s1, 297
	s_cmp_lt_u32 s0, 6
	s_cselect_b32 s0, 220, s1
	s_cmp_ge_u32 s25, s0
	s_cbranch_scc1 .LBB0_370
.LBB0_324:
	s_mov_b32 s101, s25
	v_readlane_b32 s0, v238, 16
	s_and_b32 s41, s0, 7
	s_cmp_gt_u32 s41, 5
	s_cbranch_scc1 .Lun_67
	s_cmpk_lt_u32 s25, 0xc6
	s_cbranch_scc0 .Lun_hi
	s_mul_i32 s0, s25, 0x5556
	s_lshr_b32 s26, s0, 16
	s_mul_i32 s2, s26, 3
	s_sub_i32 s2, s25, s2
	s_mul_i32 s0, s2, 6
	s_add_i32 s0, s0, s41
	s_branch .Lpp_body
.Lun_hi:
	s_sub_i32 s3, s25, 0xc6
	s_lshr_b32 s0, s3, 1
	s_and_b32 s2, s3, 1
	s_mul_i32 s1, s41, 11
	s_add_i32 s1, s0, s1
	s_cmp_eq_u32 s2, 0
	s_cselect_b32 s2, 42, 47
	s_branch .Lsg_map
.Lun_67:
	s_movk_i32 s4, 0x84
	s_cmp_eq_u32 s41, 6
	s_cselect_b32 s4, 0xa5, s4
	s_cselect_b32 s5, 4, 43
	s_cmp_lt_u32 s25, s4
	s_cselect_b32 s3, s25, 0
	s_cselect_b32 s6, 0, 33
	s_cbranch_scc1 .Lun_a
	s_sub_i32 s3, s25, s4
.Lun_a:
	s_cmp_lt_u32 s25, s4
	s_cselect_b32 s0, 1, 0
	s_cmp_eq_u32 s41, 6
	s_cselect_b32 s1, 1, 0
	s_cmp_eq_u32 s0, s1
	s_cbranch_scc1 .Lun_five
	s_lshr_b32 s1, s3, 2
	s_and_b32 s2, s3, 3
	s_branch .Lun_b
.Lun_five:
	s_mul_i32 s1, s3, 0x3334
	s_lshr_b32 s1, s1, 16
	s_mul_i32 s2, s1, 5
	s_sub_i32 s2, s3, s2
.Lun_b:
	s_add_i32 s1, s1, s6
	s_cmp_eq_u32 s2, 4
	s_cbranch_scc0 .Lun_c
	s_mov_b32 s26, s1
	s_movk_i32 s0, 18
	s_branch .Lpp_body
.Lun_c:
	s_add_i32 s2, s2, s5
